# NSA sliding-window branch on 16x16x32 tiles with the fused two-group step, two tiles of loads in flight, K reads before staging; vwT key permutation follows the new operand layout; no q reload between
# baseline (speedup 1.0000x reference)
.LBB0_851:
	s_and_b32 s4, s2, 0xff
	s_mul_hi_u32 s4, s4, 0x5555556
	s_mulk_i32 s4, 0xffd0
	s_mul_i32 s5, s65, 0xab
	s_add_i32 s80, s65, s4
	s_ashr_i32 s66, s80, 3
	s_lshr_b32 s4, s5, 10
	s_and_b32 s5, s65, 7
	s_and_b32 s4, s4, 56
	s_or_b32 s5, s5, s3
	s_ashr_i32 s67, s66, 31
	s_add_i32 s4, s4, s5
	s_lshl_b64 s[6:7], s[66:67], 18
	v_lshl_add_u64 v[124:125], v[100:101], 0, s[6:7]
	s_lshl_b32 s10, s4, 18
	s_movk_i32 s5, 0x2000
	v_lshl_add_u64 v[26:27], v[112:113], 0, s[10:11]
	v_add_co_u32_e32 v22, vcc, s5, v124
	v_lshl_add_u64 v[2:3], v[26:27], 0, v[114:115]
	v_lshl_add_u64 v[10:11], v[26:27], 0, v[116:117]
	v_addc_co_u32_e32 v23, vcc, 0, v125, vcc
	v_lshl_add_u64 v[18:19], v[26:27], 0, v[118:119]
	v_lshl_add_u64 v[26:27], v[26:27], 0, v[120:121]
	s_barrier
	global_load_dwordx4 v[2:5], v[2:3], off
	s_movk_i32 s5, 0x4000
	global_load_dwordx4 v[6:9], v[124:125], off
	global_load_dwordx4 v[14:17], v[22:23], off offset:-4096
	v_add_co_u32_e32 v34, vcc, s5, v124
	global_load_dwordx4 v[10:13], v[10:11], off
	s_nop 0
	v_addc_co_u32_e32 v35, vcc, 0, v125, vcc
	global_load_dwordx4 v[18:21], v[18:19], off
	s_add_u32 s6, s92, s10
	global_load_dwordx4 v[22:25], v[22:23], off
	s_addc_u32 s7, s93, 0
	global_load_dwordx4 v[26:29], v[26:27], off
	v_lshl_add_u64 v[126:127], s[6:7], 0, v[122:123]
	global_load_dwordx4 v[30:33], v[34:35], off offset:-4096
	s_mov_b64 s[6:7], 0x4000
	s_movk_i32 s5, 0x6000
	s_cmp_gt_i32 s66, 1
	s_cselect_b64 s[70:71], -1, 0
	s_cmp_eq_u32 s66, 2
	s_cselect_b64 s[68:69], -1, 0
	s_waitcnt vmcnt(7)
	ds_write_b128 v105, v[2:5]
	s_waitcnt vmcnt(6)
	ds_write_b128 v105, v[6:9] offset:18432
	s_waitcnt vmcnt(5)
	ds_write_b128 v109, v[14:17] offset:18432
	global_load_dwordx4 v[6:9], v[34:35], off
	s_waitcnt vmcnt(5)
	ds_write_b128 v109, v[10:13]
	s_waitcnt vmcnt(4)
	ds_write_b128 v111, v[18:21]
	s_waitcnt vmcnt(3)
	ds_write_b128 v111, v[22:25] offset:18432
	v_add_co_u32_e32 v22, vcc, s5, v124
	s_waitcnt vmcnt(2)
	ds_write_b128 v167, v[26:29]
	v_lshl_add_u64 v[26:27], v[126:127], 0, s[6:7]
	v_lshl_add_u64 v[2:3], v[26:27], 0, v[114:115]
	global_load_dwordx4 v[2:5], v[2:3], off
	v_addc_co_u32_e32 v23, vcc, 0, v125, vcc
	s_mov_b32 s5, 0x8000
	v_add_co_u32_e32 v38, vcc, s5, v124
	v_lshl_add_u64 v[10:11], v[26:27], 0, v[116:117]
	v_lshl_add_u64 v[18:19], v[26:27], 0, v[118:119]
	v_lshl_add_u64 v[26:27], v[26:27], 0, v[120:121]
	v_addc_co_u32_e32 v39, vcc, 0, v125, vcc
	s_waitcnt vmcnt(2)
	ds_write_b128 v167, v[30:33] offset:18432
	global_load_dwordx4 v[10:13], v[10:11], off
	s_mov_b32 s5, 0xc000
	global_load_dwordx4 v[14:17], v[22:23], off offset:-4096
	global_load_dwordx4 v[30:33], v[38:39], off offset:-4096
	s_mov_b64 s[6:7], 0x8000
	global_load_dwordx4 v[18:21], v[18:19], off
	v_add_co_u32_e32 v128, vcc, s5, v124
	global_load_dwordx4 v[22:25], v[22:23], off
	s_nop 0
	v_addc_co_u32_e32 v129, vcc, 0, v125, vcc
	global_load_dwordx4 v[26:29], v[26:27], off
	s_waitcnt lgkmcnt(0)
	s_barrier
	ds_read_b128 v[130:133], v172 offset:18432
	ds_read_b128 v[34:37], v173
	s_waitcnt lgkmcnt(0)
	v_mfma_f32_32x32x16_bf16 v[50:65], v[130:133], v[34:37], 0
	ds_read_b128 v[134:137], v172 offset:23040
	ds_read_b128 v[138:141], v173 offset:4608
	global_load_dwordx4 v[90:93], v[38:39], off
	s_mov_b32 s5, 0xa000
	global_load_dwordx4 v[66:69], v[128:129], off offset:-4096
	s_waitcnt lgkmcnt(1)
	v_mfma_f32_32x32x16_bf16 v[34:49], v[134:137], v[34:37], 0
	s_waitcnt vmcnt(9)
	ds_write_b128 v105, v[6:9] offset:55296
	s_waitcnt vmcnt(8)
	ds_write_b128 v105, v[2:5] offset:36864
	v_lshl_add_u64 v[2:3], v[126:127], 0, s[6:7]
	v_lshl_add_u64 v[4:5], v[2:3], 0, v[120:121]
	global_load_dwordx4 v[70:73], v[4:5], off
	v_add_co_u32_e32 v4, vcc, s5, v124
	s_mov_b32 s5, 0x9000
	s_nop 0
	v_addc_co_u32_e32 v5, vcc, 0, v125, vcc
	global_load_dwordx4 v[74:77], v[4:5], off
	v_lshl_add_u64 v[4:5], v[2:3], 0, v[118:119]
	global_load_dwordx4 v[78:81], v[4:5], off
	v_add_co_u32_e32 v4, vcc, s5, v124
	s_waitcnt vmcnt(10)
	ds_write_b128 v109, v[10:13] offset:36864
	v_addc_co_u32_e32 v5, vcc, 0, v125, vcc
	global_load_dwordx4 v[82:85], v[4:5], off
	v_lshl_add_u64 v[4:5], v[2:3], 0, v[116:117]
	v_lshl_add_u64 v[2:3], v[2:3], 0, v[114:115]
	global_load_dwordx4 v[86:89], v[4:5], off
	global_load_dwordx4 v[94:97], v[2:3], off
	s_waitcnt vmcnt(12)
	ds_write_b128 v109, v[14:17] offset:55296
	s_waitcnt lgkmcnt(4)
	v_mfma_f32_32x32x16_bf16 v[2:17], v[134:137], v[138:141], 0
	s_waitcnt vmcnt(10)
	ds_write_b128 v111, v[18:21] offset:36864
	s_waitcnt vmcnt(9)
	ds_write_b128 v111, v[22:25] offset:55296
	s_waitcnt vmcnt(8)
	ds_write_b128 v167, v[26:29] offset:36864
	ds_write_b128 v167, v[30:33] offset:55296
	s_mov_b32 s5, 0x10000
	s_mov_b64 s[6:7], 0xc000
	v_mfma_f32_32x32x16_bf16 v[18:33], v[130:133], v[138:141], 0
	ds_read_b128 v[142:145], v169 offset:23072
	ds_read_b128 v[146:149], v170 offset:4640
	s_waitcnt lgkmcnt(0)
	v_mfma_f32_32x32x16_bf16 v[2:17], v[142:145], v[146:149], v[2:17]
	ds_read_b128 v[130:133], v169 offset:18464
	ds_read_b128 v[134:137], v169 offset:18496
	s_waitcnt lgkmcnt(1)
	v_mfma_f32_32x32x16_bf16 v[18:33], v[130:133], v[146:149], v[18:33]
	ds_read_b128 v[138:141], v170 offset:32
	ds_read_b128 v[150:153], v170 offset:64
	s_waitcnt lgkmcnt(1)
	v_mfma_f32_32x32x16_bf16 v[50:65], v[130:133], v[138:141], v[50:65]
	ds_read_b128 v[154:157], v169 offset:23104
	ds_read_b128 v[158:161], v170 offset:4672
	v_mfma_f32_32x32x16_bf16 v[34:49], v[142:145], v[138:141], v[34:49]
	ds_read_b128 v[130:133], v169 offset:18528
	ds_read_b128 v[138:141], v170 offset:96
	s_waitcnt lgkmcnt(4)
	v_mfma_f32_32x32x16_bf16 v[50:65], v[134:137], v[150:153], v[50:65]
	ds_read_b128 v[142:145], v169 offset:23136
	ds_read_b128 v[146:149], v170 offset:4704
	s_waitcnt lgkmcnt(0)
	s_barrier
	v_mfma_f32_32x32x16_bf16 v[34:49], v[154:157], v[150:153], v[34:49]
	ds_read_b128 v[150:153], v173 offset:36864
	v_mfma_f32_32x32x16_bf16 v[18:33], v[134:137], v[158:161], v[18:33]
	ds_read_b128 v[134:137], v172 offset:55296
	v_mfma_f32_32x32x16_bf16 v[2:17], v[154:157], v[158:161], v[2:17]
	ds_read_b128 v[154:157], v172 offset:59904
	ds_read_b128 v[158:161], v173 offset:41472
	v_mfma_f32_32x32x16_bf16 v[50:65], v[130:133], v[138:141], v[50:65]
	s_waitcnt vmcnt(7)
	ds_write_b128 v105, v[90:93] offset:18432
	v_add_co_u32_e32 v90, vcc, s5, v124
	s_mov_b32 s5, 0xe000
	s_nop 0
	v_addc_co_u32_e32 v91, vcc, 0, v125, vcc
	s_waitcnt vmcnt(0)
	ds_write_b128 v105, v[94:97]
	v_mfma_f32_32x32x16_bf16 v[34:49], v[142:145], v[138:141], v[34:49]
	ds_write_b128 v109, v[86:89]
	ds_write_b128 v109, v[82:85] offset:18432
	v_lshl_add_u64 v[96:97], v[126:127], 0, s[6:7]
	v_lshl_add_u64 v[86:87], v[96:97], 0, v[116:117]
	global_load_dwordx4 v[92:95], v[128:129], off
	s_mov_b64 s[6:7], 0x10000
	global_load_dwordx4 v[86:89], v[86:87], off
	v_mfma_f32_32x32x16_bf16 v[18:33], v[130:133], v[146:149], v[18:33]
	ds_write_b128 v111, v[74:77] offset:18432
	v_add_co_u32_e32 v74, vcc, s5, v124
	ds_write_b128 v111, v[78:81]
	s_nop 0
	v_addc_co_u32_e32 v75, vcc, 0, v125, vcc
	v_lshl_add_u64 v[78:79], v[96:97], 0, v[118:119]
	v_mfma_f32_32x32x16_bf16 v[2:17], v[142:145], v[146:149], v[2:17]
	ds_write_b128 v167, v[70:73]
	v_lshl_add_u64 v[70:71], v[96:97], 0, v[120:121]
	s_mov_b32 s5, 0xd000
	v_lshl_add_u64 v[96:97], v[96:97], 0, v[114:115]
	v_add_co_u32_e32 v82, vcc, s5, v124
	global_load_dwordx4 v[128:131], v[96:97], off
	s_nop 0
	v_addc_co_u32_e32 v83, vcc, 0, v125, vcc
	global_load_dwordx4 v[74:77], v[74:75], off
	ds_write_b128 v167, v[66:69] offset:18432
	global_load_dwordx4 v[82:85], v[82:83], off
	s_waitcnt lgkmcnt(10)
	v_mfma_f32_32x32x16_bf16 v[50:65], v[134:137], v[150:153], v[50:65]
	global_load_dwordx4 v[70:73], v[70:71], off
	ds_read_b128 v[138:141], v169 offset:59936
	global_load_dwordx4 v[78:81], v[78:79], off
	ds_read_b128 v[142:145], v170 offset:41504
	global_load_dwordx4 v[66:69], v[90:91], off offset:-4096
	s_mov_b32 s5, 0x14000
	s_waitcnt lgkmcnt(11)
	v_mfma_f32_32x32x16_bf16 v[34:49], v[154:157], v[150:153], v[34:49]
	ds_read_b128 v[146:149], v169 offset:55360
	ds_read_b128 v[150:153], v170 offset:36896
	s_waitcnt lgkmcnt(12)
	v_mfma_f32_32x32x16_bf16 v[18:33], v[134:137], v[158:161], v[18:33]
	ds_read_b128 v[132:135], v169 offset:55328
	ds_read_b128 v[162:165], v170 offset:41536
	v_mfma_f32_32x32x16_bf16 v[2:17], v[154:157], v[158:161], v[2:17]
	ds_read_b128 v[154:157], v170 offset:36928
	ds_read_b128 v[158:161], v169 offset:59968
	s_waitcnt lgkmcnt(3)
	v_mfma_f32_32x32x16_bf16 v[50:65], v[132:135], v[150:153], v[50:65]
	v_mfma_f32_32x32x16_bf16 v[34:49], v[138:141], v[150:153], v[34:49]
	ds_read_b128 v[150:153], v170 offset:41568
	v_mfma_f32_32x32x16_bf16 v[18:33], v[132:135], v[142:145], v[18:33]
	ds_read_b128 v[132:135], v169 offset:55392
	v_mfma_f32_32x32x16_bf16 v[2:17], v[138:141], v[142:145], v[2:17]
	ds_read_b128 v[136:139], v170 offset:36960
	ds_read_b128 v[140:143], v169 offset:60000
	s_waitcnt lgkmcnt(0)
	s_barrier
	v_mfma_f32_32x32x16_bf16 v[50:65], v[146:149], v[154:157], v[50:65]
	v_mfma_f32_32x32x16_bf16 v[34:49], v[158:161], v[154:157], v[34:49]
	ds_read_b128 v[154:157], v173
	v_mfma_f32_32x32x16_bf16 v[18:33], v[146:149], v[162:165], v[18:33]
	ds_read_b128 v[144:147], v172 offset:18432
	v_mfma_f32_32x32x16_bf16 v[2:17], v[158:161], v[162:165], v[2:17]
	ds_read_b128 v[158:161], v172 offset:23040
	ds_read_b128 v[162:165], v173 offset:4608
	v_mfma_f32_32x32x16_bf16 v[50:65], v[132:135], v[136:139], v[50:65]
	s_waitcnt vmcnt(5)
	ds_write_b128 v105, v[128:131] offset:36864
	v_add_co_u32_e32 v128, vcc, s5, v124
	s_mov_b32 s5, 0x12000
	s_nop 0
	v_addc_co_u32_e32 v129, vcc, 0, v125, vcc
	ds_write_b128 v105, v[92:95] offset:55296
	v_mfma_f32_32x32x16_bf16 v[34:49], v[140:143], v[136:139], v[34:49]
	ds_write_b128 v109, v[86:89] offset:36864
	s_waitcnt vmcnt(3)
	ds_write_b128 v109, v[82:85] offset:55296
	v_lshl_add_u64 v[94:95], v[126:127], 0, s[6:7]
	v_lshl_add_u64 v[86:87], v[94:95], 0, v[116:117]
	global_load_dwordx4 v[86:89], v[86:87], off
	s_mov_b64 s[6:7], 0x14000
	global_load_dwordx4 v[90:93], v[90:91], off
	v_mfma_f32_32x32x16_bf16 v[18:33], v[132:135], v[150:153], v[18:33]
	ds_write_b128 v111, v[74:77] offset:55296
	v_add_co_u32_e32 v74, vcc, s5, v124
	s_mov_b32 s5, 0x11000
	s_nop 0
	v_addc_co_u32_e32 v75, vcc, 0, v125, vcc
	v_add_co_u32_e32 v82, vcc, s5, v124
	s_waitcnt vmcnt(3)
	ds_write_b128 v111, v[78:81] offset:36864
	v_mfma_f32_32x32x16_bf16 v[2:17], v[140:143], v[150:153], v[2:17]
	ds_write_b128 v167, v[70:73] offset:36864
	v_lshl_add_u64 v[70:71], v[94:95], 0, v[120:121]
	v_lshl_add_u64 v[78:79], v[94:95], 0, v[118:119]
	v_addc_co_u32_e32 v83, vcc, 0, v125, vcc
	v_lshl_add_u64 v[94:95], v[94:95], 0, v[114:115]
	global_load_dwordx4 v[82:85], v[82:83], off
	s_waitcnt vmcnt(3)
	ds_write_b128 v167, v[66:69] offset:55296
	global_load_dwordx4 v[94:97], v[94:95], off
	s_waitcnt lgkmcnt(10)
	v_mfma_f32_32x32x16_bf16 v[50:65], v[144:147], v[154:157], v[50:65]
	global_load_dwordx4 v[74:77], v[74:75], off
	ds_read_b128 v[130:133], v169 offset:23072
	global_load_dwordx4 v[70:73], v[70:71], off
	ds_read_b128 v[134:137], v170 offset:4640
	global_load_dwordx4 v[78:81], v[78:79], off
	s_mov_b32 s5, 0x18000
	global_load_dwordx4 v[66:69], v[128:129], off offset:-4096
	s_waitcnt lgkmcnt(11)
	v_mfma_f32_32x32x16_bf16 v[34:49], v[158:161], v[154:157], v[34:49]
	ds_read_b128 v[138:141], v169 offset:18464
	ds_read_b128 v[150:153], v170 offset:64
	s_waitcnt lgkmcnt(12)
	v_mfma_f32_32x32x16_bf16 v[18:33], v[144:147], v[162:165], v[18:33]
	ds_read_b128 v[146:149], v170 offset:32
	ds_read_b128 v[142:145], v169 offset:18496
	v_mfma_f32_32x32x16_bf16 v[2:17], v[158:161], v[162:165], v[2:17]
	ds_read_b128 v[154:157], v169 offset:23104
	ds_read_b128 v[158:161], v170 offset:4672
	s_waitcnt lgkmcnt(3)
	v_mfma_f32_32x32x16_bf16 v[50:65], v[138:141], v[146:149], v[50:65]
	v_mfma_f32_32x32x16_bf16 v[34:49], v[130:133], v[146:149], v[34:49]
	ds_read_b128 v[146:149], v170 offset:4704
	v_mfma_f32_32x32x16_bf16 v[18:33], v[138:141], v[134:137], v[18:33]
	ds_read_b128 v[138:141], v169 offset:23136
	v_mfma_f32_32x32x16_bf16 v[2:17], v[130:133], v[134:137], v[2:17]
	ds_read_b128 v[130:133], v169 offset:18528
	ds_read_b128 v[134:137], v170 offset:96
	s_waitcnt lgkmcnt(0)
	s_barrier
	v_mfma_f32_32x32x16_bf16 v[50:65], v[142:145], v[150:153], v[50:65]
	v_mfma_f32_32x32x16_bf16 v[34:49], v[154:157], v[150:153], v[34:49]
	ds_read_b128 v[150:153], v173 offset:36864
	v_mfma_f32_32x32x16_bf16 v[18:33], v[142:145], v[158:161], v[18:33]
	ds_read_b128 v[142:145], v172 offset:55296
	v_mfma_f32_32x32x16_bf16 v[2:17], v[154:157], v[158:161], v[2:17]
	ds_read_b128 v[154:157], v172 offset:59904
	ds_read_b128 v[158:161], v173 offset:41472
	v_mfma_f32_32x32x16_bf16 v[50:65], v[130:133], v[134:137], v[50:65]
	s_waitcnt vmcnt(4)
	ds_write_b128 v105, v[94:97]
	ds_write_b128 v105, v[90:93] offset:18432
	v_lshl_add_u64 v[94:95], v[126:127], 0, s[6:7]
	global_load_dwordx4 v[90:93], v[128:129], off
	s_mov_b64 s[6:7], 0x18000
	v_mfma_f32_32x32x16_bf16 v[34:49], v[138:141], v[134:137], v[34:49]
	ds_write_b128 v109, v[86:89]
	ds_write_b128 v109, v[82:85] offset:18432
	v_lshl_add_u64 v[86:87], v[94:95], 0, v[116:117]
	global_load_dwordx4 v[86:89], v[86:87], off
	v_mfma_f32_32x32x16_bf16 v[18:33], v[130:133], v[146:149], v[18:33]
	v_add_co_u32_e32 v130, vcc, s5, v124
	s_mov_b32 s5, 0x16000
	s_nop 0
	v_addc_co_u32_e32 v131, vcc, 0, v125, vcc
	s_waitcnt vmcnt(5)
	ds_write_b128 v111, v[74:77] offset:18432
	v_add_co_u32_e32 v74, vcc, s5, v124
	s_mov_b32 s5, 0x15000
	s_nop 0
	v_addc_co_u32_e32 v75, vcc, 0, v125, vcc
	v_add_co_u32_e32 v82, vcc, s5, v124
	s_waitcnt vmcnt(3)
	ds_write_b128 v111, v[78:81]
	v_mfma_f32_32x32x16_bf16 v[2:17], v[138:141], v[146:149], v[2:17]
	ds_write_b128 v167, v[70:73]
	v_lshl_add_u64 v[70:71], v[94:95], 0, v[120:121]
	v_lshl_add_u64 v[78:79], v[94:95], 0, v[118:119]
	v_addc_co_u32_e32 v83, vcc, 0, v125, vcc
	v_lshl_add_u64 v[94:95], v[94:95], 0, v[114:115]
	global_load_dwordx4 v[74:77], v[74:75], off
	s_waitcnt vmcnt(3)
	ds_write_b128 v167, v[66:69] offset:18432
	global_load_dwordx4 v[82:85], v[82:83], off
	s_waitcnt lgkmcnt(10)
	v_mfma_f32_32x32x16_bf16 v[50:65], v[142:145], v[150:153], v[50:65]
	global_load_dwordx4 v[94:97], v[94:95], off
	ds_read_b128 v[132:135], v169 offset:59936
	global_load_dwordx4 v[70:73], v[70:71], off
	ds_read_b128 v[136:139], v170 offset:41504
	global_load_dwordx4 v[78:81], v[78:79], off
	s_mov_b32 s5, 0x1c000
	global_load_dwordx4 v[66:69], v[130:131], off offset:-4096
	s_waitcnt lgkmcnt(11)
	v_mfma_f32_32x32x16_bf16 v[34:49], v[154:157], v[150:153], v[34:49]
	ds_read_b128 v[148:151], v170 offset:36896
	v_add_co_u32_e32 v128, vcc, s5, v124
	s_mov_b32 s5, 0x1a000
	s_nop 0
	v_addc_co_u32_e32 v129, vcc, 0, v125, vcc
	s_waitcnt lgkmcnt(11)
	v_mfma_f32_32x32x16_bf16 v[18:33], v[142:145], v[158:161], v[18:33]
	ds_read_b128 v[140:143], v169 offset:55328
	ds_read_b128 v[144:147], v169 offset:55360
	v_mfma_f32_32x32x16_bf16 v[2:17], v[154:157], v[158:161], v[2:17]
	ds_read_b128 v[156:159], v169 offset:59968
	ds_read_b128 v[152:155], v170 offset:36928
	s_waitcnt lgkmcnt(3)
	v_mfma_f32_32x32x16_bf16 v[50:65], v[140:143], v[148:151], v[50:65]
	ds_read_b128 v[160:163], v170 offset:41536
	v_mfma_f32_32x32x16_bf16 v[34:49], v[132:135], v[148:151], v[34:49]
	ds_read_b128 v[148:151], v170 offset:41568
	v_mfma_f32_32x32x16_bf16 v[18:33], v[140:143], v[136:139], v[18:33]
	ds_read_b128 v[140:143], v169 offset:60000
	v_mfma_f32_32x32x16_bf16 v[2:17], v[132:135], v[136:139], v[2:17]
	ds_read_b128 v[132:135], v169 offset:55392
	ds_read_b128 v[136:139], v170 offset:36960
	s_waitcnt lgkmcnt(0)
	s_barrier
	v_mfma_f32_32x32x16_bf16 v[50:65], v[144:147], v[152:155], v[50:65]
	v_mfma_f32_32x32x16_bf16 v[34:49], v[156:159], v[152:155], v[34:49]
	ds_read_b128 v[152:155], v173
	v_mfma_f32_32x32x16_bf16 v[18:33], v[144:147], v[160:163], v[18:33]
	ds_read_b128 v[144:147], v172 offset:18432
	v_mfma_f32_32x32x16_bf16 v[2:17], v[156:159], v[160:163], v[2:17]
	ds_read_b128 v[156:159], v172 offset:23040
	ds_read_b128 v[160:163], v173 offset:4608
	v_mfma_f32_32x32x16_bf16 v[50:65], v[132:135], v[136:139], v[50:65]
	s_waitcnt vmcnt(3)
	ds_write_b128 v105, v[94:97] offset:36864
	ds_write_b128 v105, v[90:93] offset:55296
	v_lshl_add_u64 v[94:95], v[126:127], 0, s[6:7]
	global_load_dwordx4 v[90:93], v[130:131], off
	s_mov_b64 s[6:7], 0x1c000
	v_mfma_f32_32x32x16_bf16 v[34:49], v[140:143], v[136:139], v[34:49]
	ds_write_b128 v109, v[86:89] offset:36864
	ds_write_b128 v109, v[82:85] offset:55296
	v_lshl_add_u64 v[86:87], v[94:95], 0, v[116:117]
	global_load_dwordx4 v[86:89], v[86:87], off
	v_mfma_f32_32x32x16_bf16 v[18:33], v[132:135], v[148:151], v[18:33]
	ds_write_b128 v111, v[74:77] offset:55296
	v_add_co_u32_e32 v74, vcc, s5, v124
	s_mov_b32 s5, 0x19000
	s_nop 0
	v_addc_co_u32_e32 v75, vcc, 0, v125, vcc
	v_add_co_u32_e32 v82, vcc, s5, v124
	s_waitcnt vmcnt(3)
	ds_write_b128 v111, v[78:81] offset:36864
	v_mfma_f32_32x32x16_bf16 v[2:17], v[140:143], v[148:151], v[2:17]
	ds_write_b128 v167, v[70:73] offset:36864
	v_lshl_add_u64 v[70:71], v[94:95], 0, v[120:121]
	v_lshl_add_u64 v[78:79], v[94:95], 0, v[118:119]
	v_addc_co_u32_e32 v83, vcc, 0, v125, vcc
	v_lshl_add_u64 v[94:95], v[94:95], 0, v[114:115]
	global_load_dwordx4 v[82:85], v[82:83], off
	s_waitcnt vmcnt(3)
	ds_write_b128 v167, v[66:69] offset:55296
	global_load_dwordx4 v[94:97], v[94:95], off
	s_waitcnt lgkmcnt(10)
	v_mfma_f32_32x32x16_bf16 v[50:65], v[144:147], v[152:155], v[50:65]
	global_load_dwordx4 v[74:77], v[74:75], off
	ds_read_b128 v[130:133], v169 offset:23072
	global_load_dwordx4 v[70:73], v[70:71], off
	ds_read_b128 v[134:137], v170 offset:4640
	global_load_dwordx4 v[78:81], v[78:79], off
	s_mov_b32 s5, 0x20000
	global_load_dwordx4 v[66:69], v[128:129], off offset:-4096
	s_waitcnt lgkmcnt(11)
	v_mfma_f32_32x32x16_bf16 v[34:49], v[156:159], v[152:155], v[34:49]
	ds_read_b128 v[138:141], v169 offset:18464
	ds_read_b128 v[150:153], v170 offset:64
	s_waitcnt lgkmcnt(12)
	v_mfma_f32_32x32x16_bf16 v[18:33], v[144:147], v[160:163], v[18:33]
	ds_read_b128 v[146:149], v170 offset:32
	ds_read_b128 v[142:145], v169 offset:18496
	v_mfma_f32_32x32x16_bf16 v[2:17], v[156:159], v[160:163], v[2:17]
	ds_read_b128 v[154:157], v169 offset:23104
	ds_read_b128 v[158:161], v170 offset:4672
	s_waitcnt lgkmcnt(3)
	v_mfma_f32_32x32x16_bf16 v[50:65], v[138:141], v[146:149], v[50:65]
	v_mfma_f32_32x32x16_bf16 v[34:49], v[130:133], v[146:149], v[34:49]
	ds_read_b128 v[146:149], v170 offset:4704
	v_mfma_f32_32x32x16_bf16 v[18:33], v[138:141], v[134:137], v[18:33]
	ds_read_b128 v[138:141], v169 offset:23136
	v_mfma_f32_32x32x16_bf16 v[2:17], v[130:133], v[134:137], v[2:17]
	ds_read_b128 v[130:133], v169 offset:18528
	ds_read_b128 v[134:137], v170 offset:96
	s_waitcnt lgkmcnt(0)
	s_barrier
	v_mfma_f32_32x32x16_bf16 v[50:65], v[142:145], v[150:153], v[50:65]
	v_mfma_f32_32x32x16_bf16 v[34:49], v[154:157], v[150:153], v[34:49]
	ds_read_b128 v[150:153], v173 offset:36864
	v_mfma_f32_32x32x16_bf16 v[18:33], v[142:145], v[158:161], v[18:33]
	ds_read_b128 v[142:145], v172 offset:55296
	v_mfma_f32_32x32x16_bf16 v[2:17], v[154:157], v[158:161], v[2:17]
	ds_read_b128 v[154:157], v172 offset:59904
	ds_read_b128 v[158:161], v173 offset:41472
	v_mfma_f32_32x32x16_bf16 v[50:65], v[130:133], v[134:137], v[50:65]
	s_waitcnt vmcnt(4)
	ds_write_b128 v105, v[94:97]
	ds_write_b128 v105, v[90:93] offset:18432
	v_lshl_add_u64 v[94:95], v[126:127], 0, s[6:7]
	global_load_dwordx4 v[90:93], v[128:129], off
	s_mov_b64 s[6:7], 0x20000
	v_mfma_f32_32x32x16_bf16 v[34:49], v[138:141], v[134:137], v[34:49]
	ds_write_b128 v109, v[86:89]
	ds_write_b128 v109, v[82:85] offset:18432
	v_lshl_add_u64 v[86:87], v[94:95], 0, v[116:117]
	global_load_dwordx4 v[86:89], v[86:87], off
	v_mfma_f32_32x32x16_bf16 v[18:33], v[130:133], v[146:149], v[18:33]
	v_add_co_u32_e32 v130, vcc, s5, v124
	s_mov_b32 s5, 0x1e000
	s_nop 0
	v_addc_co_u32_e32 v131, vcc, 0, v125, vcc
	s_waitcnt vmcnt(5)
	ds_write_b128 v111, v[74:77] offset:18432
	v_add_co_u32_e32 v74, vcc, s5, v124
	s_mov_b32 s5, 0x1d000
	s_nop 0
	v_addc_co_u32_e32 v75, vcc, 0, v125, vcc
	v_add_co_u32_e32 v82, vcc, s5, v124
	s_waitcnt vmcnt(3)
	ds_write_b128 v111, v[78:81]
	v_mfma_f32_32x32x16_bf16 v[2:17], v[138:141], v[146:149], v[2:17]
	ds_write_b128 v167, v[70:73]
	v_lshl_add_u64 v[70:71], v[94:95], 0, v[120:121]
	v_lshl_add_u64 v[78:79], v[94:95], 0, v[118:119]
	v_addc_co_u32_e32 v83, vcc, 0, v125, vcc
	v_lshl_add_u64 v[94:95], v[94:95], 0, v[114:115]
	global_load_dwordx4 v[74:77], v[74:75], off
	s_waitcnt vmcnt(3)
	ds_write_b128 v167, v[66:69] offset:18432
	global_load_dwordx4 v[82:85], v[82:83], off
	s_waitcnt lgkmcnt(10)
	v_mfma_f32_32x32x16_bf16 v[50:65], v[142:145], v[150:153], v[50:65]
	global_load_dwordx4 v[94:97], v[94:95], off
	ds_read_b128 v[132:135], v169 offset:59936
	global_load_dwordx4 v[70:73], v[70:71], off
	ds_read_b128 v[136:139], v170 offset:41504
	global_load_dwordx4 v[78:81], v[78:79], off
	s_mov_b32 s5, 0x24000
	global_load_dwordx4 v[66:69], v[130:131], off offset:-4096
	s_waitcnt lgkmcnt(11)
	v_mfma_f32_32x32x16_bf16 v[34:49], v[154:157], v[150:153], v[34:49]
	ds_read_b128 v[148:151], v170 offset:36896
	v_add_co_u32_e32 v128, vcc, s5, v124
	s_mov_b32 s5, 0x22000
	s_nop 0
	v_addc_co_u32_e32 v129, vcc, 0, v125, vcc
	s_waitcnt lgkmcnt(11)
	v_mfma_f32_32x32x16_bf16 v[18:33], v[142:145], v[158:161], v[18:33]
	ds_read_b128 v[140:143], v169 offset:55328
	ds_read_b128 v[144:147], v169 offset:55360
	v_mfma_f32_32x32x16_bf16 v[2:17], v[154:157], v[158:161], v[2:17]
	ds_read_b128 v[156:159], v169 offset:59968
	ds_read_b128 v[152:155], v170 offset:36928
	s_waitcnt lgkmcnt(3)
	v_mfma_f32_32x32x16_bf16 v[50:65], v[140:143], v[148:151], v[50:65]
	ds_read_b128 v[160:163], v170 offset:41536
	v_mfma_f32_32x32x16_bf16 v[34:49], v[132:135], v[148:151], v[34:49]
	ds_read_b128 v[148:151], v170 offset:41568
	v_mfma_f32_32x32x16_bf16 v[18:33], v[140:143], v[136:139], v[18:33]
	ds_read_b128 v[140:143], v169 offset:60000
	v_mfma_f32_32x32x16_bf16 v[2:17], v[132:135], v[136:139], v[2:17]
	ds_read_b128 v[132:135], v169 offset:55392
	ds_read_b128 v[136:139], v170 offset:36960
	s_waitcnt lgkmcnt(0)
	s_barrier
	v_mfma_f32_32x32x16_bf16 v[50:65], v[144:147], v[152:155], v[50:65]
	v_mfma_f32_32x32x16_bf16 v[34:49], v[156:159], v[152:155], v[34:49]
	ds_read_b128 v[152:155], v173
	v_mfma_f32_32x32x16_bf16 v[18:33], v[144:147], v[160:163], v[18:33]
	ds_read_b128 v[144:147], v172 offset:18432
	v_mfma_f32_32x32x16_bf16 v[2:17], v[156:159], v[160:163], v[2:17]
	ds_read_b128 v[156:159], v172 offset:23040
	ds_read_b128 v[160:163], v173 offset:4608
	v_mfma_f32_32x32x16_bf16 v[50:65], v[132:135], v[136:139], v[50:65]
	s_waitcnt vmcnt(3)
	ds_write_b128 v105, v[94:97] offset:36864
	ds_write_b128 v105, v[90:93] offset:55296
	v_lshl_add_u64 v[94:95], v[126:127], 0, s[6:7]
	global_load_dwordx4 v[90:93], v[130:131], off
	s_mov_b64 s[6:7], 0x24000
	v_mfma_f32_32x32x16_bf16 v[34:49], v[140:143], v[136:139], v[34:49]
	ds_write_b128 v109, v[86:89] offset:36864
	ds_write_b128 v109, v[82:85] offset:55296
	v_lshl_add_u64 v[86:87], v[94:95], 0, v[116:117]
	global_load_dwordx4 v[86:89], v[86:87], off
	v_mfma_f32_32x32x16_bf16 v[18:33], v[132:135], v[148:151], v[18:33]
	ds_write_b128 v111, v[74:77] offset:55296
	v_add_co_u32_e32 v74, vcc, s5, v124
	s_mov_b32 s5, 0x21000
	s_nop 0
	v_addc_co_u32_e32 v75, vcc, 0, v125, vcc
	v_add_co_u32_e32 v82, vcc, s5, v124
	s_waitcnt vmcnt(3)
	ds_write_b128 v111, v[78:81] offset:36864
	v_mfma_f32_32x32x16_bf16 v[2:17], v[140:143], v[148:151], v[2:17]
	ds_write_b128 v167, v[70:73] offset:36864
	v_lshl_add_u64 v[70:71], v[94:95], 0, v[120:121]
	v_lshl_add_u64 v[78:79], v[94:95], 0, v[118:119]
	v_addc_co_u32_e32 v83, vcc, 0, v125, vcc
	v_lshl_add_u64 v[94:95], v[94:95], 0, v[114:115]
	global_load_dwordx4 v[82:85], v[82:83], off
	s_waitcnt vmcnt(3)
	ds_write_b128 v167, v[66:69] offset:55296
	global_load_dwordx4 v[94:97], v[94:95], off
	s_waitcnt lgkmcnt(10)
	v_mfma_f32_32x32x16_bf16 v[50:65], v[144:147], v[152:155], v[50:65]
	global_load_dwordx4 v[74:77], v[74:75], off
	ds_read_b128 v[130:133], v169 offset:23072
	global_load_dwordx4 v[70:73], v[70:71], off
	ds_read_b128 v[134:137], v170 offset:4640
	global_load_dwordx4 v[78:81], v[78:79], off
	s_mov_b32 s5, 0x28000
	global_load_dwordx4 v[66:69], v[128:129], off offset:-4096
	s_waitcnt lgkmcnt(11)
	v_mfma_f32_32x32x16_bf16 v[34:49], v[156:159], v[152:155], v[34:49]
	ds_read_b128 v[138:141], v169 offset:18464
	ds_read_b128 v[150:153], v170 offset:64
	s_waitcnt lgkmcnt(12)
	v_mfma_f32_32x32x16_bf16 v[18:33], v[144:147], v[160:163], v[18:33]
	ds_read_b128 v[146:149], v170 offset:32
	ds_read_b128 v[142:145], v169 offset:18496
	v_mfma_f32_32x32x16_bf16 v[2:17], v[156:159], v[160:163], v[2:17]
	ds_read_b128 v[154:157], v169 offset:23104
	ds_read_b128 v[158:161], v170 offset:4672
	s_waitcnt lgkmcnt(3)
	v_mfma_f32_32x32x16_bf16 v[50:65], v[138:141], v[146:149], v[50:65]
	v_mfma_f32_32x32x16_bf16 v[34:49], v[130:133], v[146:149], v[34:49]
	ds_read_b128 v[146:149], v170 offset:4704
	v_mfma_f32_32x32x16_bf16 v[18:33], v[138:141], v[134:137], v[18:33]
	ds_read_b128 v[138:141], v169 offset:23136
	v_mfma_f32_32x32x16_bf16 v[2:17], v[130:133], v[134:137], v[2:17]
	ds_read_b128 v[130:133], v169 offset:18528
	ds_read_b128 v[134:137], v170 offset:96
	s_waitcnt lgkmcnt(0)
	s_barrier
	v_mfma_f32_32x32x16_bf16 v[50:65], v[142:145], v[150:153], v[50:65]
	v_mfma_f32_32x32x16_bf16 v[34:49], v[154:157], v[150:153], v[34:49]
	ds_read_b128 v[150:153], v173 offset:36864
	v_mfma_f32_32x32x16_bf16 v[18:33], v[142:145], v[158:161], v[18:33]
	ds_read_b128 v[142:145], v172 offset:55296
	v_mfma_f32_32x32x16_bf16 v[2:17], v[154:157], v[158:161], v[2:17]
	ds_read_b128 v[154:157], v172 offset:59904
	ds_read_b128 v[158:161], v173 offset:41472
	v_mfma_f32_32x32x16_bf16 v[50:65], v[130:133], v[134:137], v[50:65]
	s_waitcnt vmcnt(4)
	ds_write_b128 v105, v[94:97]
	ds_write_b128 v105, v[90:93] offset:18432
	v_lshl_add_u64 v[94:95], v[126:127], 0, s[6:7]
	global_load_dwordx4 v[90:93], v[128:129], off
	s_mov_b64 s[6:7], 0x28000
	v_mfma_f32_32x32x16_bf16 v[34:49], v[138:141], v[134:137], v[34:49]
	ds_write_b128 v109, v[86:89]
	ds_write_b128 v109, v[82:85] offset:18432
	v_lshl_add_u64 v[86:87], v[94:95], 0, v[116:117]
	global_load_dwordx4 v[86:89], v[86:87], off
	v_mfma_f32_32x32x16_bf16 v[18:33], v[130:133], v[146:149], v[18:33]
	v_add_co_u32_e32 v130, vcc, s5, v124
	s_mov_b32 s5, 0x26000
	s_nop 0
	v_addc_co_u32_e32 v131, vcc, 0, v125, vcc
	s_waitcnt vmcnt(5)
	ds_write_b128 v111, v[74:77] offset:18432
	v_add_co_u32_e32 v74, vcc, s5, v124
	s_mov_b32 s5, 0x25000
	s_nop 0
	v_addc_co_u32_e32 v75, vcc, 0, v125, vcc
	v_add_co_u32_e32 v82, vcc, s5, v124
	s_waitcnt vmcnt(3)
	ds_write_b128 v111, v[78:81]
	v_mfma_f32_32x32x16_bf16 v[2:17], v[138:141], v[146:149], v[2:17]
	ds_write_b128 v167, v[70:73]
	v_lshl_add_u64 v[70:71], v[94:95], 0, v[120:121]
	v_lshl_add_u64 v[78:79], v[94:95], 0, v[118:119]
	v_addc_co_u32_e32 v83, vcc, 0, v125, vcc
	v_lshl_add_u64 v[94:95], v[94:95], 0, v[114:115]
	global_load_dwordx4 v[74:77], v[74:75], off
	s_waitcnt vmcnt(3)
	ds_write_b128 v167, v[66:69] offset:18432
	global_load_dwordx4 v[82:85], v[82:83], off
	s_waitcnt lgkmcnt(10)
	v_mfma_f32_32x32x16_bf16 v[50:65], v[142:145], v[150:153], v[50:65]
	global_load_dwordx4 v[94:97], v[94:95], off
	ds_read_b128 v[132:135], v169 offset:59936
	global_load_dwordx4 v[70:73], v[70:71], off
	ds_read_b128 v[136:139], v170 offset:41504
	global_load_dwordx4 v[78:81], v[78:79], off
	s_mov_b32 s5, 0x2c000
	global_load_dwordx4 v[66:69], v[130:131], off offset:-4096
	s_waitcnt lgkmcnt(11)
	v_mfma_f32_32x32x16_bf16 v[34:49], v[154:157], v[150:153], v[34:49]
	ds_read_b128 v[148:151], v170 offset:36896
	v_add_co_u32_e32 v128, vcc, s5, v124
	s_mov_b32 s5, 0x2a000
	s_nop 0
	v_addc_co_u32_e32 v129, vcc, 0, v125, vcc
	s_waitcnt lgkmcnt(11)
	v_mfma_f32_32x32x16_bf16 v[18:33], v[142:145], v[158:161], v[18:33]
	ds_read_b128 v[140:143], v169 offset:55328
	ds_read_b128 v[144:147], v169 offset:55360
	v_mfma_f32_32x32x16_bf16 v[2:17], v[154:157], v[158:161], v[2:17]
	ds_read_b128 v[156:159], v169 offset:59968
	ds_read_b128 v[152:155], v170 offset:36928
	s_waitcnt lgkmcnt(3)
	v_mfma_f32_32x32x16_bf16 v[50:65], v[140:143], v[148:151], v[50:65]
	ds_read_b128 v[160:163], v170 offset:41536
	v_mfma_f32_32x32x16_bf16 v[34:49], v[132:135], v[148:151], v[34:49]
	ds_read_b128 v[148:151], v170 offset:41568
	v_mfma_f32_32x32x16_bf16 v[18:33], v[140:143], v[136:139], v[18:33]
	ds_read_b128 v[140:143], v169 offset:60000
	v_mfma_f32_32x32x16_bf16 v[2:17], v[132:135], v[136:139], v[2:17]
	ds_read_b128 v[132:135], v169 offset:55392
	ds_read_b128 v[136:139], v170 offset:36960
	s_waitcnt lgkmcnt(0)
	s_barrier
	v_mfma_f32_32x32x16_bf16 v[50:65], v[144:147], v[152:155], v[50:65]
	v_mfma_f32_32x32x16_bf16 v[34:49], v[156:159], v[152:155], v[34:49]
	ds_read_b128 v[152:155], v173
	v_mfma_f32_32x32x16_bf16 v[18:33], v[144:147], v[160:163], v[18:33]
	ds_read_b128 v[144:147], v172 offset:18432
	v_mfma_f32_32x32x16_bf16 v[2:17], v[156:159], v[160:163], v[2:17]
	ds_read_b128 v[156:159], v172 offset:23040
	ds_read_b128 v[160:163], v173 offset:4608
	v_mfma_f32_32x32x16_bf16 v[50:65], v[132:135], v[136:139], v[50:65]
	s_waitcnt vmcnt(3)
	ds_write_b128 v105, v[94:97] offset:36864
	ds_write_b128 v105, v[90:93] offset:55296
	v_lshl_add_u64 v[94:95], v[126:127], 0, s[6:7]
	global_load_dwordx4 v[90:93], v[130:131], off
	s_mov_b64 s[6:7], 0x2c000
	v_mfma_f32_32x32x16_bf16 v[34:49], v[140:143], v[136:139], v[34:49]
	ds_write_b128 v109, v[86:89] offset:36864
	ds_write_b128 v109, v[82:85] offset:55296
	v_lshl_add_u64 v[86:87], v[94:95], 0, v[116:117]
	global_load_dwordx4 v[86:89], v[86:87], off
	v_mfma_f32_32x32x16_bf16 v[18:33], v[132:135], v[148:151], v[18:33]
	ds_write_b128 v111, v[74:77] offset:55296
	v_add_co_u32_e32 v74, vcc, s5, v124
	s_mov_b32 s5, 0x29000
	s_nop 0
	v_addc_co_u32_e32 v75, vcc, 0, v125, vcc
	v_add_co_u32_e32 v82, vcc, s5, v124
	s_waitcnt vmcnt(3)
	ds_write_b128 v111, v[78:81] offset:36864
	v_mfma_f32_32x32x16_bf16 v[2:17], v[140:143], v[148:151], v[2:17]
	ds_write_b128 v167, v[70:73] offset:36864
	v_lshl_add_u64 v[70:71], v[94:95], 0, v[120:121]
	v_lshl_add_u64 v[78:79], v[94:95], 0, v[118:119]
	v_addc_co_u32_e32 v83, vcc, 0, v125, vcc
	v_lshl_add_u64 v[94:95], v[94:95], 0, v[114:115]
	global_load_dwordx4 v[82:85], v[82:83], off
	s_waitcnt vmcnt(3)
	ds_write_b128 v167, v[66:69] offset:55296
	global_load_dwordx4 v[94:97], v[94:95], off
	s_waitcnt lgkmcnt(10)
	v_mfma_f32_32x32x16_bf16 v[50:65], v[144:147], v[152:155], v[50:65]
	global_load_dwordx4 v[74:77], v[74:75], off
	ds_read_b128 v[130:133], v169 offset:23072
	global_load_dwordx4 v[70:73], v[70:71], off
	ds_read_b128 v[134:137], v170 offset:4640
	global_load_dwordx4 v[78:81], v[78:79], off
	s_mov_b32 s5, 0x30000
	global_load_dwordx4 v[66:69], v[128:129], off offset:-4096
	s_waitcnt lgkmcnt(11)
	v_mfma_f32_32x32x16_bf16 v[34:49], v[156:159], v[152:155], v[34:49]
	ds_read_b128 v[138:141], v169 offset:18464
	ds_read_b128 v[150:153], v170 offset:64
	s_waitcnt lgkmcnt(12)
	v_mfma_f32_32x32x16_bf16 v[18:33], v[144:147], v[160:163], v[18:33]
	ds_read_b128 v[146:149], v170 offset:32
	ds_read_b128 v[142:145], v169 offset:18496
	v_mfma_f32_32x32x16_bf16 v[2:17], v[156:159], v[160:163], v[2:17]
	ds_read_b128 v[154:157], v169 offset:23104
	ds_read_b128 v[158:161], v170 offset:4672
	s_waitcnt lgkmcnt(3)
	v_mfma_f32_32x32x16_bf16 v[50:65], v[138:141], v[146:149], v[50:65]
	v_mfma_f32_32x32x16_bf16 v[34:49], v[130:133], v[146:149], v[34:49]
	ds_read_b128 v[146:149], v170 offset:4704
	v_mfma_f32_32x32x16_bf16 v[18:33], v[138:141], v[134:137], v[18:33]
	ds_read_b128 v[138:141], v169 offset:23136
	v_mfma_f32_32x32x16_bf16 v[2:17], v[130:133], v[134:137], v[2:17]
	ds_read_b128 v[130:133], v169 offset:18528
	ds_read_b128 v[134:137], v170 offset:96
	s_waitcnt lgkmcnt(0)
	s_barrier
	v_mfma_f32_32x32x16_bf16 v[50:65], v[142:145], v[150:153], v[50:65]
	v_mfma_f32_32x32x16_bf16 v[34:49], v[154:157], v[150:153], v[34:49]
	ds_read_b128 v[150:153], v173 offset:36864
	v_mfma_f32_32x32x16_bf16 v[18:33], v[142:145], v[158:161], v[18:33]
	ds_read_b128 v[142:145], v172 offset:55296
	v_mfma_f32_32x32x16_bf16 v[2:17], v[154:157], v[158:161], v[2:17]
	ds_read_b128 v[154:157], v172 offset:59904
	ds_read_b128 v[158:161], v173 offset:41472
	v_mfma_f32_32x32x16_bf16 v[50:65], v[130:133], v[134:137], v[50:65]
	s_waitcnt vmcnt(4)
	ds_write_b128 v105, v[94:97]
	ds_write_b128 v105, v[90:93] offset:18432
	v_lshl_add_u64 v[94:95], v[126:127], 0, s[6:7]
	global_load_dwordx4 v[90:93], v[128:129], off
	s_mov_b64 s[6:7], 0x30000
	v_mfma_f32_32x32x16_bf16 v[34:49], v[138:141], v[134:137], v[34:49]
	ds_write_b128 v109, v[86:89]
	ds_write_b128 v109, v[82:85] offset:18432
	v_lshl_add_u64 v[86:87], v[94:95], 0, v[116:117]
	global_load_dwordx4 v[86:89], v[86:87], off
	v_mfma_f32_32x32x16_bf16 v[18:33], v[130:133], v[146:149], v[18:33]
	v_add_co_u32_e32 v130, vcc, s5, v124
	s_mov_b32 s5, 0x2e000
	s_nop 0
	v_addc_co_u32_e32 v131, vcc, 0, v125, vcc
	s_waitcnt vmcnt(5)
	ds_write_b128 v111, v[74:77] offset:18432
	v_add_co_u32_e32 v74, vcc, s5, v124
	s_mov_b32 s5, 0x2d000
	s_nop 0
	v_addc_co_u32_e32 v75, vcc, 0, v125, vcc
	v_add_co_u32_e32 v82, vcc, s5, v124
	s_waitcnt vmcnt(3)
	ds_write_b128 v111, v[78:81]
	v_mfma_f32_32x32x16_bf16 v[2:17], v[138:141], v[146:149], v[2:17]
	ds_write_b128 v167, v[70:73]
	v_lshl_add_u64 v[70:71], v[94:95], 0, v[120:121]
	v_lshl_add_u64 v[78:79], v[94:95], 0, v[118:119]
	v_addc_co_u32_e32 v83, vcc, 0, v125, vcc
	v_lshl_add_u64 v[94:95], v[94:95], 0, v[114:115]
	global_load_dwordx4 v[74:77], v[74:75], off
	s_waitcnt vmcnt(3)
	ds_write_b128 v167, v[66:69] offset:18432
	global_load_dwordx4 v[82:85], v[82:83], off
	s_waitcnt lgkmcnt(10)
	v_mfma_f32_32x32x16_bf16 v[50:65], v[142:145], v[150:153], v[50:65]
	global_load_dwordx4 v[94:97], v[94:95], off
	ds_read_b128 v[132:135], v169 offset:59936
	global_load_dwordx4 v[70:73], v[70:71], off
	ds_read_b128 v[136:139], v170 offset:41504
	global_load_dwordx4 v[78:81], v[78:79], off
	s_mov_b32 s5, 0x34000
	global_load_dwordx4 v[66:69], v[130:131], off offset:-4096
	s_waitcnt lgkmcnt(11)
	v_mfma_f32_32x32x16_bf16 v[34:49], v[154:157], v[150:153], v[34:49]
	ds_read_b128 v[148:151], v170 offset:36896
	v_add_co_u32_e32 v128, vcc, s5, v124
	s_mov_b32 s5, 0x32000
	s_nop 0
	v_addc_co_u32_e32 v129, vcc, 0, v125, vcc
	s_waitcnt lgkmcnt(11)
	v_mfma_f32_32x32x16_bf16 v[18:33], v[142:145], v[158:161], v[18:33]
	ds_read_b128 v[140:143], v169 offset:55328
	ds_read_b128 v[144:147], v169 offset:55360
	v_mfma_f32_32x32x16_bf16 v[2:17], v[154:157], v[158:161], v[2:17]
	ds_read_b128 v[156:159], v169 offset:59968
	ds_read_b128 v[152:155], v170 offset:36928
	s_waitcnt lgkmcnt(3)
	v_mfma_f32_32x32x16_bf16 v[50:65], v[140:143], v[148:151], v[50:65]
	ds_read_b128 v[160:163], v170 offset:41536
	v_mfma_f32_32x32x16_bf16 v[34:49], v[132:135], v[148:151], v[34:49]
	ds_read_b128 v[148:151], v170 offset:41568
	v_mfma_f32_32x32x16_bf16 v[18:33], v[140:143], v[136:139], v[18:33]
	ds_read_b128 v[140:143], v169 offset:60000
	v_mfma_f32_32x32x16_bf16 v[2:17], v[132:135], v[136:139], v[2:17]
	ds_read_b128 v[132:135], v169 offset:55392
	ds_read_b128 v[136:139], v170 offset:36960
	s_waitcnt lgkmcnt(0)
	s_barrier
	v_mfma_f32_32x32x16_bf16 v[50:65], v[144:147], v[152:155], v[50:65]
	v_mfma_f32_32x32x16_bf16 v[34:49], v[156:159], v[152:155], v[34:49]
	ds_read_b128 v[152:155], v173
	v_mfma_f32_32x32x16_bf16 v[18:33], v[144:147], v[160:163], v[18:33]
	ds_read_b128 v[144:147], v172 offset:18432
	v_mfma_f32_32x32x16_bf16 v[2:17], v[156:159], v[160:163], v[2:17]
	ds_read_b128 v[156:159], v172 offset:23040
	ds_read_b128 v[160:163], v173 offset:4608
	v_mfma_f32_32x32x16_bf16 v[50:65], v[132:135], v[136:139], v[50:65]
	s_waitcnt vmcnt(3)
	ds_write_b128 v105, v[94:97] offset:36864
	ds_write_b128 v105, v[90:93] offset:55296
	v_lshl_add_u64 v[94:95], v[126:127], 0, s[6:7]
	global_load_dwordx4 v[90:93], v[130:131], off
	s_mov_b64 s[6:7], 0x34000
	v_mfma_f32_32x32x16_bf16 v[34:49], v[140:143], v[136:139], v[34:49]
	ds_write_b128 v109, v[86:89] offset:36864
	ds_write_b128 v109, v[82:85] offset:55296
	v_lshl_add_u64 v[86:87], v[94:95], 0, v[116:117]
	global_load_dwordx4 v[86:89], v[86:87], off
	v_mfma_f32_32x32x16_bf16 v[18:33], v[132:135], v[148:151], v[18:33]
	ds_write_b128 v111, v[74:77] offset:55296
	v_add_co_u32_e32 v74, vcc, s5, v124
	s_mov_b32 s5, 0x31000
	s_nop 0
	v_addc_co_u32_e32 v75, vcc, 0, v125, vcc
	v_add_co_u32_e32 v82, vcc, s5, v124
	s_waitcnt vmcnt(3)
	ds_write_b128 v111, v[78:81] offset:36864
	v_mfma_f32_32x32x16_bf16 v[2:17], v[140:143], v[148:151], v[2:17]
	ds_write_b128 v167, v[70:73] offset:36864
	v_lshl_add_u64 v[70:71], v[94:95], 0, v[120:121]
	v_lshl_add_u64 v[78:79], v[94:95], 0, v[118:119]
	v_addc_co_u32_e32 v83, vcc, 0, v125, vcc
	v_lshl_add_u64 v[94:95], v[94:95], 0, v[114:115]
	global_load_dwordx4 v[82:85], v[82:83], off
	s_waitcnt vmcnt(3)
	ds_write_b128 v167, v[66:69] offset:55296
	global_load_dwordx4 v[94:97], v[94:95], off
	s_waitcnt lgkmcnt(10)
	v_mfma_f32_32x32x16_bf16 v[50:65], v[144:147], v[152:155], v[50:65]
	global_load_dwordx4 v[74:77], v[74:75], off
	ds_read_b128 v[130:133], v169 offset:23072
	global_load_dwordx4 v[70:73], v[70:71], off
	ds_read_b128 v[134:137], v170 offset:4640
	global_load_dwordx4 v[78:81], v[78:79], off
	s_mov_b32 s5, 0x38000
	global_load_dwordx4 v[66:69], v[128:129], off offset:-4096
	s_waitcnt lgkmcnt(11)
	v_mfma_f32_32x32x16_bf16 v[34:49], v[156:159], v[152:155], v[34:49]
	ds_read_b128 v[138:141], v169 offset:18464
	ds_read_b128 v[150:153], v170 offset:64
	s_waitcnt lgkmcnt(12)
	v_mfma_f32_32x32x16_bf16 v[18:33], v[144:147], v[160:163], v[18:33]
	ds_read_b128 v[146:149], v170 offset:32
	ds_read_b128 v[142:145], v169 offset:18496
	v_mfma_f32_32x32x16_bf16 v[2:17], v[156:159], v[160:163], v[2:17]
	ds_read_b128 v[154:157], v169 offset:23104
	ds_read_b128 v[158:161], v170 offset:4672
	s_waitcnt lgkmcnt(3)
	v_mfma_f32_32x32x16_bf16 v[50:65], v[138:141], v[146:149], v[50:65]
	v_mfma_f32_32x32x16_bf16 v[34:49], v[130:133], v[146:149], v[34:49]
	ds_read_b128 v[146:149], v170 offset:4704
	v_mfma_f32_32x32x16_bf16 v[18:33], v[138:141], v[134:137], v[18:33]
	ds_read_b128 v[138:141], v169 offset:23136
	v_mfma_f32_32x32x16_bf16 v[2:17], v[130:133], v[134:137], v[2:17]
	ds_read_b128 v[130:133], v169 offset:18528
	ds_read_b128 v[134:137], v170 offset:96
	s_waitcnt lgkmcnt(0)
	s_barrier
	v_mfma_f32_32x32x16_bf16 v[50:65], v[142:145], v[150:153], v[50:65]
	v_mfma_f32_32x32x16_bf16 v[34:49], v[154:157], v[150:153], v[34:49]
	ds_read_b128 v[150:153], v173 offset:36864
	v_mfma_f32_32x32x16_bf16 v[18:33], v[142:145], v[158:161], v[18:33]
	ds_read_b128 v[142:145], v172 offset:55296
	v_mfma_f32_32x32x16_bf16 v[2:17], v[154:157], v[158:161], v[2:17]
	ds_read_b128 v[154:157], v172 offset:59904
	ds_read_b128 v[158:161], v173 offset:41472
	v_mfma_f32_32x32x16_bf16 v[50:65], v[130:133], v[134:137], v[50:65]
	s_waitcnt vmcnt(4)
	ds_write_b128 v105, v[94:97]
	ds_write_b128 v105, v[90:93] offset:18432
	v_lshl_add_u64 v[94:95], v[126:127], 0, s[6:7]
	global_load_dwordx4 v[90:93], v[128:129], off
	s_mov_b64 s[6:7], 0x38000
	v_mfma_f32_32x32x16_bf16 v[34:49], v[138:141], v[134:137], v[34:49]
	ds_write_b128 v109, v[86:89]
	ds_write_b128 v109, v[82:85] offset:18432
	v_lshl_add_u64 v[86:87], v[94:95], 0, v[116:117]
	global_load_dwordx4 v[86:89], v[86:87], off
	v_mfma_f32_32x32x16_bf16 v[18:33], v[130:133], v[146:149], v[18:33]
	v_add_co_u32_e32 v130, vcc, s5, v124
	s_mov_b32 s5, 0x36000
	s_nop 0
	v_addc_co_u32_e32 v131, vcc, 0, v125, vcc
	s_waitcnt vmcnt(5)
	ds_write_b128 v111, v[74:77] offset:18432
	v_add_co_u32_e32 v74, vcc, s5, v124
	s_mov_b32 s5, 0x35000
	s_nop 0
	v_addc_co_u32_e32 v75, vcc, 0, v125, vcc
	v_add_co_u32_e32 v82, vcc, s5, v124
	s_waitcnt vmcnt(3)
	ds_write_b128 v111, v[78:81]
	v_mfma_f32_32x32x16_bf16 v[2:17], v[138:141], v[146:149], v[2:17]
	ds_write_b128 v167, v[70:73]
	v_lshl_add_u64 v[70:71], v[94:95], 0, v[120:121]
	v_lshl_add_u64 v[78:79], v[94:95], 0, v[118:119]
	v_addc_co_u32_e32 v83, vcc, 0, v125, vcc
	v_lshl_add_u64 v[94:95], v[94:95], 0, v[114:115]
	global_load_dwordx4 v[74:77], v[74:75], off
	s_waitcnt vmcnt(3)
	ds_write_b128 v167, v[66:69] offset:18432
	global_load_dwordx4 v[82:85], v[82:83], off
	s_waitcnt lgkmcnt(10)
	v_mfma_f32_32x32x16_bf16 v[50:65], v[142:145], v[150:153], v[50:65]
	global_load_dwordx4 v[94:97], v[94:95], off
	ds_read_b128 v[132:135], v169 offset:59936
	global_load_dwordx4 v[70:73], v[70:71], off
	ds_read_b128 v[136:139], v170 offset:41504
	global_load_dwordx4 v[78:81], v[78:79], off
	s_mov_b32 s5, 0x3c000
	global_load_dwordx4 v[66:69], v[130:131], off offset:-4096
	s_waitcnt lgkmcnt(11)
	v_mfma_f32_32x32x16_bf16 v[34:49], v[154:157], v[150:153], v[34:49]
	ds_read_b128 v[148:151], v170 offset:36896
	v_add_co_u32_e32 v128, vcc, s5, v124
	s_mov_b32 s5, 0x3a000
	s_nop 0
	v_addc_co_u32_e32 v129, vcc, 0, v125, vcc
	s_waitcnt lgkmcnt(11)
	v_mfma_f32_32x32x16_bf16 v[18:33], v[142:145], v[158:161], v[18:33]
	ds_read_b128 v[140:143], v169 offset:55328
	ds_read_b128 v[144:147], v169 offset:55360
	v_mfma_f32_32x32x16_bf16 v[2:17], v[154:157], v[158:161], v[2:17]
	ds_read_b128 v[156:159], v169 offset:59968
	ds_read_b128 v[152:155], v170 offset:36928
	s_waitcnt lgkmcnt(3)
	v_mfma_f32_32x32x16_bf16 v[50:65], v[140:143], v[148:151], v[50:65]
	ds_read_b128 v[160:163], v170 offset:41536
	v_mfma_f32_32x32x16_bf16 v[34:49], v[132:135], v[148:151], v[34:49]
	ds_read_b128 v[148:151], v170 offset:41568
	v_mfma_f32_32x32x16_bf16 v[18:33], v[140:143], v[136:139], v[18:33]
	ds_read_b128 v[140:143], v169 offset:60000
	v_mfma_f32_32x32x16_bf16 v[2:17], v[132:135], v[136:139], v[2:17]
	ds_read_b128 v[132:135], v169 offset:55392
	ds_read_b128 v[136:139], v170 offset:36960
	s_waitcnt lgkmcnt(0)
	s_barrier
	v_mfma_f32_32x32x16_bf16 v[50:65], v[144:147], v[152:155], v[50:65]
	v_mfma_f32_32x32x16_bf16 v[34:49], v[156:159], v[152:155], v[34:49]
	ds_read_b128 v[152:155], v173
	v_mfma_f32_32x32x16_bf16 v[18:33], v[144:147], v[160:163], v[18:33]
	ds_read_b128 v[144:147], v172 offset:18432
	v_mfma_f32_32x32x16_bf16 v[2:17], v[156:159], v[160:163], v[2:17]
	ds_read_b128 v[156:159], v172 offset:23040
	ds_read_b128 v[160:163], v173 offset:4608
	v_mfma_f32_32x32x16_bf16 v[50:65], v[132:135], v[136:139], v[50:65]
	s_waitcnt vmcnt(3)
	ds_write_b128 v105, v[94:97] offset:36864
	ds_write_b128 v105, v[90:93] offset:55296
	v_lshl_add_u64 v[94:95], v[126:127], 0, s[6:7]
	global_load_dwordx4 v[90:93], v[130:131], off
	s_mov_b64 s[6:7], 0x3c000
	v_mfma_f32_32x32x16_bf16 v[34:49], v[140:143], v[136:139], v[34:49]
	ds_write_b128 v109, v[86:89] offset:36864
	ds_write_b128 v109, v[82:85] offset:55296
	v_lshl_add_u64 v[86:87], v[94:95], 0, v[116:117]
	global_load_dwordx4 v[86:89], v[86:87], off
	v_mfma_f32_32x32x16_bf16 v[18:33], v[132:135], v[148:151], v[18:33]
	ds_write_b128 v111, v[74:77] offset:55296
	v_add_co_u32_e32 v74, vcc, s5, v124
	s_mov_b32 s5, 0x39000
	s_nop 0
	v_addc_co_u32_e32 v75, vcc, 0, v125, vcc
	v_add_co_u32_e32 v82, vcc, s5, v124
	s_waitcnt vmcnt(3)
	ds_write_b128 v111, v[78:81] offset:36864
	v_mfma_f32_32x32x16_bf16 v[2:17], v[140:143], v[148:151], v[2:17]
	ds_write_b128 v167, v[70:73] offset:36864
	v_lshl_add_u64 v[70:71], v[94:95], 0, v[120:121]
	v_lshl_add_u64 v[78:79], v[94:95], 0, v[118:119]
	v_addc_co_u32_e32 v83, vcc, 0, v125, vcc
	v_lshl_add_u64 v[94:95], v[94:95], 0, v[114:115]
	s_waitcnt vmcnt(2)
	ds_write_b128 v167, v[66:69] offset:55296
	global_load_dwordx4 v[66:69], v[128:129], off offset:-4096
	s_waitcnt lgkmcnt(10)
	v_mfma_f32_32x32x16_bf16 v[50:65], v[144:147], v[152:155], v[50:65]
	global_load_dwordx4 v[74:77], v[74:75], off
	ds_read_b128 v[130:133], v169 offset:23072
	global_load_dwordx4 v[78:81], v[78:79], off
	ds_read_b128 v[134:137], v170 offset:4640
	global_load_dwordx4 v[82:85], v[82:83], off
	s_mov_b32 s5, 0x3f000
	global_load_dwordx4 v[94:97], v[94:95], off
	s_waitcnt lgkmcnt(11)
	v_mfma_f32_32x32x16_bf16 v[34:49], v[156:159], v[152:155], v[34:49]
	global_load_dwordx4 v[70:73], v[70:71], off
	ds_read_b128 v[138:141], v169 offset:18464
	ds_read_b128 v[150:153], v170 offset:64
	s_waitcnt lgkmcnt(12)
	v_mfma_f32_32x32x16_bf16 v[18:33], v[144:147], v[160:163], v[18:33]
	ds_read_b128 v[142:145], v169 offset:18496
	ds_read_b128 v[146:149], v170 offset:32
	v_mfma_f32_32x32x16_bf16 v[2:17], v[156:159], v[160:163], v[2:17]
	ds_read_b128 v[154:157], v169 offset:23104
	ds_read_b128 v[158:161], v170 offset:4672
	s_waitcnt lgkmcnt(2)
	v_mfma_f32_32x32x16_bf16 v[50:65], v[138:141], v[146:149], v[50:65]
	v_mfma_f32_32x32x16_bf16 v[34:49], v[130:133], v[146:149], v[34:49]
	ds_read_b128 v[146:149], v170 offset:4704
	v_mfma_f32_32x32x16_bf16 v[18:33], v[138:141], v[134:137], v[18:33]
	ds_read_b128 v[138:141], v169 offset:23136
	v_mfma_f32_32x32x16_bf16 v[2:17], v[130:133], v[134:137], v[2:17]
	ds_read_b128 v[130:133], v169 offset:18528
	ds_read_b128 v[134:137], v170 offset:96
	s_waitcnt lgkmcnt(0)
	s_barrier
	v_mfma_f32_32x32x16_bf16 v[50:65], v[142:145], v[150:153], v[50:65]
	v_mfma_f32_32x32x16_bf16 v[34:49], v[154:157], v[150:153], v[34:49]
	ds_read_b128 v[150:153], v173 offset:36864
	v_mfma_f32_32x32x16_bf16 v[18:33], v[142:145], v[158:161], v[18:33]
	ds_read_b128 v[142:145], v172 offset:55296
	v_mfma_f32_32x32x16_bf16 v[2:17], v[154:157], v[158:161], v[2:17]
	ds_read_b128 v[154:157], v172 offset:59904
	ds_read_b128 v[158:161], v173 offset:41472
	v_mfma_f32_32x32x16_bf16 v[50:65], v[130:133], v[134:137], v[50:65]
	s_waitcnt vmcnt(1)
	ds_write_b128 v105, v[94:97]
	ds_write_b128 v105, v[90:93] offset:18432
	v_lshl_add_u64 v[94:95], v[126:127], 0, s[6:7]
	global_load_dwordx4 v[90:93], v[128:129], off
	v_mfma_f32_32x32x16_bf16 v[34:49], v[138:141], v[134:137], v[34:49]
	ds_write_b128 v109, v[86:89]
	ds_write_b128 v109, v[82:85] offset:18432
	v_lshl_add_u64 v[86:87], v[94:95], 0, v[116:117]
	global_load_dwordx4 v[86:89], v[86:87], off
	v_mfma_f32_32x32x16_bf16 v[18:33], v[130:133], v[146:149], v[18:33]
	ds_write_b128 v111, v[78:81]
	ds_write_b128 v111, v[74:77] offset:18432
	v_lshl_add_u64 v[78:79], v[94:95], 0, v[118:119]
	global_load_dwordx4 v[78:81], v[78:79], off
	v_mfma_f32_32x32x16_bf16 v[2:17], v[138:141], v[146:149], v[2:17]
	ds_write_b128 v167, v[66:69] offset:18432
	v_add_co_u32_e32 v66, vcc, s5, v124
	s_mov_b32 s5, 0x3e000
	s_nop 0
	v_addc_co_u32_e32 v67, vcc, 0, v125, vcc
	v_add_co_u32_e32 v74, vcc, s5, v124
	s_mov_b32 s5, 0x3d000
	s_nop 0
	v_addc_co_u32_e32 v75, vcc, 0, v125, vcc
	s_waitcnt vmcnt(3)
	ds_write_b128 v167, v[70:73]
	v_lshl_add_u64 v[70:71], v[94:95], 0, v[120:121]
	v_add_co_u32_e32 v82, vcc, s5, v124
	v_lshl_add_u64 v[94:95], v[94:95], 0, v[114:115]
	s_nop 0
	v_addc_co_u32_e32 v83, vcc, 0, v125, vcc
	global_load_dwordx4 v[94:97], v[94:95], off
	s_waitcnt lgkmcnt(10)
	v_mfma_f32_32x32x16_bf16 v[50:65], v[142:145], v[150:153], v[50:65]
	global_load_dwordx4 v[82:85], v[82:83], off
	ds_read_b128 v[124:127], v169 offset:59936
	global_load_dwordx4 v[74:77], v[74:75], off
	ds_read_b128 v[128:131], v170 offset:41504
	global_load_dwordx4 v[66:69], v[66:67], off
	s_nop 0
	global_load_dwordx4 v[70:73], v[70:71], off
	s_waitcnt lgkmcnt(11)
	v_mfma_f32_32x32x16_bf16 v[34:49], v[154:157], v[150:153], v[34:49]
	ds_read_b128 v[132:135], v169 offset:55328
	ds_read_b128 v[136:139], v169 offset:55360
	s_waitcnt lgkmcnt(12)
	v_mfma_f32_32x32x16_bf16 v[18:33], v[142:145], v[158:161], v[18:33]
	ds_read_b128 v[140:143], v170 offset:36896
	ds_read_b128 v[144:147], v170 offset:36928
	v_mfma_f32_32x32x16_bf16 v[2:17], v[154:157], v[158:161], v[2:17]
	ds_read_b128 v[148:151], v169 offset:59968
	ds_read_b128 v[152:155], v170 offset:41536
	s_waitcnt lgkmcnt(3)
	v_mfma_f32_32x32x16_bf16 v[50:65], v[132:135], v[140:143], v[50:65]
	v_mfma_f32_32x32x16_bf16 v[34:49], v[124:127], v[140:143], v[34:49]
	ds_read_b128 v[140:143], v170 offset:41568
	v_mfma_f32_32x32x16_bf16 v[18:33], v[132:135], v[128:131], v[18:33]
	ds_read_b128 v[132:135], v169 offset:60000
	v_mfma_f32_32x32x16_bf16 v[2:17], v[124:127], v[128:131], v[2:17]
	ds_read_b128 v[124:127], v169 offset:55392
	ds_read_b128 v[128:131], v170 offset:36960
	s_waitcnt lgkmcnt(0)
	s_barrier
	v_mfma_f32_32x32x16_bf16 v[50:65], v[136:139], v[144:147], v[50:65]
	v_mfma_f32_32x32x16_bf16 v[34:49], v[148:151], v[144:147], v[34:49]
	ds_read_b128 v[144:147], v173
	v_mfma_f32_32x32x16_bf16 v[18:33], v[136:139], v[152:155], v[18:33]
	ds_read_b128 v[136:139], v172 offset:18432
	v_mfma_f32_32x32x16_bf16 v[2:17], v[148:151], v[152:155], v[2:17]
	ds_read_b128 v[148:151], v172 offset:23040
	ds_read_b128 v[152:155], v173 offset:4608
	v_mfma_f32_32x32x16_bf16 v[50:65], v[124:127], v[128:131], v[50:65]
	s_waitcnt vmcnt(4)
	ds_write_b128 v105, v[94:97] offset:36864
	ds_write_b128 v105, v[90:93] offset:55296
	v_mfma_f32_32x32x16_bf16 v[34:49], v[132:135], v[128:131], v[34:49]
	ds_write_b128 v109, v[86:89] offset:36864
	s_waitcnt vmcnt(3)
	ds_write_b128 v109, v[82:85] offset:55296
	v_mfma_f32_32x32x16_bf16 v[18:33], v[124:127], v[140:143], v[18:33]
	ds_write_b128 v111, v[78:81] offset:36864
	s_waitcnt vmcnt(2)
	ds_write_b128 v111, v[74:77] offset:55296
	v_lshl_add_u32 v125, s4, 7, v168
	s_movk_i32 s4, 0xfe
	v_mfma_f32_32x32x16_bf16 v[2:17], v[132:135], v[140:143], v[2:17]
	s_waitcnt vmcnt(0)
	ds_write_b128 v167, v[70:73] offset:36864
	ds_write_b128 v167, v[66:69] offset:55296
	s_waitcnt lgkmcnt(10)
	v_mfma_f32_32x32x16_bf16 v[50:65], v[136:139], v[144:147], v[50:65]
	ds_read_b128 v[66:69], v169 offset:23072
	ds_read_b128 v[70:73], v170 offset:4640
	s_waitcnt lgkmcnt(11)
	v_mfma_f32_32x32x16_bf16 v[34:49], v[148:151], v[144:147], v[34:49]
	ds_read_b128 v[74:77], v169 offset:18464
	ds_read_b128 v[78:81], v169 offset:18496
	s_waitcnt lgkmcnt(12)
	v_mfma_f32_32x32x16_bf16 v[18:33], v[136:139], v[152:155], v[18:33]
	ds_read_b128 v[82:85], v170 offset:32
	ds_read_b128 v[86:89], v170 offset:64
	v_mfma_f32_32x32x16_bf16 v[2:17], v[148:151], v[152:155], v[2:17]
	ds_read_b128 v[90:93], v169 offset:23104
	ds_read_b128 v[94:97], v170 offset:4672
	s_waitcnt lgkmcnt(3)
	v_mfma_f32_32x32x16_bf16 v[50:65], v[74:77], v[82:85], v[50:65]
	v_mfma_f32_32x32x16_bf16 v[34:49], v[66:69], v[82:85], v[34:49]
	ds_read_b128 v[82:85], v170 offset:4704
	v_mfma_f32_32x32x16_bf16 v[18:33], v[74:77], v[70:73], v[18:33]
	ds_read_b128 v[74:77], v169 offset:23136
	v_mfma_f32_32x32x16_bf16 v[2:17], v[66:69], v[70:73], v[2:17]
	ds_read_b128 v[66:69], v169 offset:18528
	ds_read_b128 v[70:73], v170 offset:96
	s_waitcnt lgkmcnt(0)
	s_barrier
	v_mfma_f32_32x32x16_bf16 v[50:65], v[78:81], v[86:89], v[50:65]
	v_mfma_f32_32x32x16_bf16 v[34:49], v[90:93], v[86:89], v[34:49]
	ds_read_b128 v[86:89], v173 offset:36864
	v_mfma_f32_32x32x16_bf16 v[18:33], v[78:81], v[94:97], v[18:33]
	ds_read_b128 v[78:81], v172 offset:55296
	v_mfma_f32_32x32x16_bf16 v[2:17], v[90:93], v[94:97], v[2:17]
	ds_read_b128 v[90:93], v172 offset:59904
	ds_read_b128 v[94:97], v173 offset:41472
	v_mfma_f32_32x32x16_bf16 v[50:65], v[66:69], v[70:73], v[50:65]
	v_mfma_f32_32x32x16_bf16 v[34:49], v[74:77], v[70:73], v[34:49]
	ds_read_b128 v[70:73], v170 offset:41504
	v_mfma_f32_32x32x16_bf16 v[18:33], v[66:69], v[82:85], v[18:33]
	ds_read_b128 v[66:69], v169 offset:59936
	v_mfma_f32_32x32x16_bf16 v[2:17], v[74:77], v[82:85], v[2:17]
	ds_read_b128 v[74:77], v169 offset:55328
	ds_read_b128 v[82:85], v170 offset:36896
	s_waitcnt lgkmcnt(6)
	v_mfma_f32_32x32x16_bf16 v[50:65], v[78:81], v[86:89], v[50:65]
	s_waitcnt lgkmcnt(5)
	v_mfma_f32_32x32x16_bf16 v[34:49], v[90:93], v[86:89], v[34:49]
	ds_read_b128 v[86:89], v170 offset:36928
	s_waitcnt lgkmcnt(5)
	v_mfma_f32_32x32x16_bf16 v[18:33], v[78:81], v[94:97], v[18:33]
	ds_read_b128 v[78:81], v169 offset:55360
	v_mfma_f32_32x32x16_bf16 v[2:17], v[90:93], v[94:97], v[2:17]
	ds_read_b128 v[90:93], v169 offset:59968
	ds_read_b128 v[94:97], v170 offset:41536
	s_waitcnt lgkmcnt(4)
	v_mfma_f32_32x32x16_bf16 v[50:65], v[74:77], v[82:85], v[50:65]
	v_mfma_f32_32x32x16_bf16 v[34:49], v[66:69], v[82:85], v[34:49]
	ds_read_b128 v[82:85], v170 offset:41568
	v_mfma_f32_32x32x16_bf16 v[18:33], v[74:77], v[70:73], v[18:33]
	ds_read_b128 v[74:77], v169 offset:60000
	v_mfma_f32_32x32x16_bf16 v[2:17], v[66:69], v[70:73], v[2:17]
	ds_read_b128 v[66:69], v169 offset:55392
	ds_read_b128 v[70:73], v170 offset:36960
	s_waitcnt lgkmcnt(0)
	s_barrier
	v_mfma_f32_32x32x16_bf16 v[50:65], v[78:81], v[86:89], v[50:65]
	v_mfma_f32_32x32x16_bf16 v[34:49], v[90:93], v[86:89], v[34:49]
	v_mfma_f32_32x32x16_bf16 v[18:33], v[78:81], v[94:97], v[18:33]
	v_mfma_f32_32x32x16_bf16 v[2:17], v[90:93], v[94:97], v[2:17]
	v_mfma_f32_32x32x16_bf16 v[50:65], v[66:69], v[70:73], v[50:65]
	v_mfma_f32_32x32x16_bf16 v[34:49], v[74:77], v[70:73], v[34:49]
	v_mfma_f32_32x32x16_bf16 v[18:33], v[66:69], v[82:85], v[18:33]
	v_lshrrev_b32_e32 v66, 12, v125
	v_and_or_b32 v179, v66, s4, v103
	v_or_b32_e32 v66, v125, v1
	v_mov_b32_e32 v67, v99
	v_lshlrev_b64 v[68:69], 6, v[66:67]
	v_lshl_add_u64 v[80:81], s[44:45], 0, v[68:69]
	global_load_dwordx4 v[68:71], v[80:81], off offset:48
	v_mfma_f32_32x32x16_bf16 v[2:17], v[74:77], v[82:85], v[2:17]
	global_load_dwordx4 v[72:75], v[80:81], off offset:32
	global_load_dwordx4 v[76:79], v[80:81], off offset:16
	s_movk_i32 s4, 0x1fdf
	global_load_dwordx4 v[80:83], v[80:81], off
	v_lshlrev_b32_e32 v98, 20, v179
	v_bitop3_b32 v180, v125, s4, v1 bitop3:0xc8
	s_mov_b64 s[4:5], -1
	s_waitcnt vmcnt(2)
	v_add_f32_e32 v72, v72, v73
	v_add_f32_e32 v74, v74, v75
	v_mov_b32_e32 v73, v70
	s_waitcnt vmcnt(0)
	v_mov_b32_e32 v84, v81
	v_mov_b32_e32 v85, v82
	v_mov_b32_e32 v81, v83
	v_mov_b32_e32 v82, v77
	v_mov_b32_e32 v83, v78
	v_mov_b32_e32 v77, v79
	v_pk_add_f32 v[80:81], v[84:85], v[80:81]
	v_pk_add_f32 v[76:77], v[82:83], v[76:77]
	v_pk_add_f32 v[80:81], v[80:81], v[80:81] op_sel:[0,1] op_sel_hi:[1,0]
	v_pk_add_f32 v[76:77], v[76:77], v[76:77] op_sel:[0,1] op_sel_hi:[1,0]
	v_mov_b32_e32 v81, v68
	v_mov_b32_e32 v77, v69
	v_mov_b32_e32 v75, v71
	v_pk_add_f32 v[68:69], v[80:81], v[76:77]
	v_pk_add_f32 v[70:71], v[72:73], v[74:75]
	s_nop 0
	v_pk_add_f32 v[68:69], v[68:69], v[70:71]
	s_nop 0
	v_add_f32_e32 v68, v68, v69
	v_fmamk_f32 v68, v68, 0x3a800000, v174
	v_cmp_gt_f32_e32 vcc, s17, v68
	v_mul_f32_e32 v69, 0x4b800000, v68
	s_nop 0
	v_cndmask_b32_e32 v68, v68, v69, vcc
	v_rsq_f32_e32 v68, v68
	s_nop 0
	v_mul_f32_e32 v69, 0x45800000, v68
	v_cndmask_b32_e32 v124, v68, v69, vcc
	s_and_b64 vcc, exec, s[70:71]
	s_cbranch_vccz .LBB0_894
	s_cmp_lt_i32 s66, 3
	s_cbranch_scc1 .LBB0_859
	s_cmp_gt_i32 s66, 3
	s_cbranch_scc0 .LBB0_857
	s_cmp_lg_u32 s66, 4
	s_cbranch_scc0 .LBB0_856
	v_readlane_b32 s4, v231, 28
	v_readlane_b32 s5, v231, 29
	v_lshlrev_b32_e32 v70, 7, v180
	v_and_b32_e32 v70, 0xfe000, v70
	v_lshl_add_u64 v[68:69], s[4:5], 0, v[98:99]
	v_mov_b32_e32 v71, v99
	v_lshl_add_u64 v[68:69], v[68:69], 0, v[70:71]
	v_lshlrev_b32_e32 v70, 1, v214
	v_lshl_add_u64 v[68:69], v[68:69], 0, v[70:71]
	v_mul_f32_e32 v70, v50, v124
	v_cvt_pk_bf16_f32 v72, v70, s0
	v_lshlrev_b32_e32 v70, 1, v102
	v_lshl_add_u64 v[68:69], v[68:69], 0, v[70:71]
	v_mul_f32_e32 v70, v51, v124
	v_cvt_pk_bf16_f32 v70, v70, s0
	global_store_short v[68:69], v70, off offset:128
	v_mul_f32_e32 v70, v52, v124
	v_cvt_pk_bf16_f32 v70, v70, s0
	global_store_short v[68:69], v70, off offset:256
	v_mul_f32_e32 v70, v53, v124
	v_cvt_pk_bf16_f32 v70, v70, s0
	global_store_short v[68:69], v70, off offset:384
	v_mul_f32_e32 v70, v54, v124
	v_cvt_pk_bf16_f32 v70, v70, s0
	global_store_short v[68:69], v70, off offset:1024
	v_mul_f32_e32 v70, v55, v124
	v_cvt_pk_bf16_f32 v70, v70, s0
	global_store_short v[68:69], v70, off offset:1152
	v_mul_f32_e32 v70, v56, v124
	v_cvt_pk_bf16_f32 v70, v70, s0
	global_store_short v[68:69], v70, off offset:1280
	v_mul_f32_e32 v70, v57, v124
	v_cvt_pk_bf16_f32 v70, v70, s0
	global_store_short v[68:69], v70, off offset:1408
	v_mul_f32_e32 v70, v58, v124
	v_cvt_pk_bf16_f32 v70, v70, s0
	global_store_short v[68:69], v70, off offset:2048
	v_mul_f32_e32 v70, v59, v124
	v_cvt_pk_bf16_f32 v70, v70, s0
	global_store_short v[68:69], v70, off offset:2176
	v_mul_f32_e32 v70, v60, v124
	v_cvt_pk_bf16_f32 v70, v70, s0
	global_store_short v[68:69], v70, off offset:2304
	v_mul_f32_e32 v70, v61, v124
	v_cvt_pk_bf16_f32 v70, v70, s0
	global_store_short v[68:69], v70, off offset:2432
	v_mul_f32_e32 v70, v62, v124
	v_cvt_pk_bf16_f32 v70, v70, s0
	global_store_short v[68:69], v70, off offset:3072
	v_mul_f32_e32 v70, v63, v124
	v_cvt_pk_bf16_f32 v70, v70, s0
	global_store_short v[68:69], v70, off offset:3200
	v_mul_f32_e32 v70, v64, v124
	v_cvt_pk_bf16_f32 v70, v70, s0
	global_store_short v[68:69], v70, off offset:3328
	v_mul_f32_e32 v70, v65, v124
	v_cvt_pk_bf16_f32 v70, v70, s0
	global_store_short v[68:69], v72, off
	global_store_short v[68:69], v70, off offset:3456
	v_mul_f32_e32 v70, v34, v124
	v_add_co_u32_e32 v68, vcc, s13, v68
	v_cvt_pk_bf16_f32 v70, v70, s0
	s_nop 0
	v_addc_co_u32_e32 v69, vcc, 0, v69, vcc
	global_store_short v[68:69], v70, off
	v_mul_f32_e32 v70, v35, v124
	v_cvt_pk_bf16_f32 v70, v70, s0
	global_store_short v[68:69], v70, off offset:128
	v_mul_f32_e32 v70, v36, v124
	v_cvt_pk_bf16_f32 v70, v70, s0
	global_store_short v[68:69], v70, off offset:256
	v_mul_f32_e32 v70, v37, v124
	v_cvt_pk_bf16_f32 v70, v70, s0
	global_store_short v[68:69], v70, off offset:384
	v_mul_f32_e32 v70, v38, v124
	v_cvt_pk_bf16_f32 v70, v70, s0
	global_store_short v[68:69], v70, off offset:1024
	v_mul_f32_e32 v70, v39, v124
	v_cvt_pk_bf16_f32 v70, v70, s0
	global_store_short v[68:69], v70, off offset:1152
	v_mul_f32_e32 v70, v40, v124
	v_cvt_pk_bf16_f32 v70, v70, s0
	global_store_short v[68:69], v70, off offset:1280
	v_mul_f32_e32 v70, v41, v124
	v_cvt_pk_bf16_f32 v70, v70, s0
	global_store_short v[68:69], v70, off offset:1408
	v_mul_f32_e32 v70, v42, v124
	v_cvt_pk_bf16_f32 v70, v70, s0
	global_store_short v[68:69], v70, off offset:2048
	v_mul_f32_e32 v70, v43, v124
	v_cvt_pk_bf16_f32 v70, v70, s0
	global_store_short v[68:69], v70, off offset:2176
	v_mul_f32_e32 v70, v44, v124
	v_cvt_pk_bf16_f32 v70, v70, s0
	global_store_short v[68:69], v70, off offset:2304
	v_mul_f32_e32 v70, v45, v124
	v_cvt_pk_bf16_f32 v70, v70, s0
	global_store_short v[68:69], v70, off offset:2432
	v_mul_f32_e32 v70, v46, v124
	v_cvt_pk_bf16_f32 v70, v70, s0
	global_store_short v[68:69], v70, off offset:3072
	v_mul_f32_e32 v70, v47, v124
	v_cvt_pk_bf16_f32 v70, v70, s0
	global_store_short v[68:69], v70, off offset:3200
	v_mul_f32_e32 v70, v48, v124
	v_cvt_pk_bf16_f32 v70, v70, s0
	global_store_short v[68:69], v70, off offset:3328
	v_mul_f32_e32 v70, v49, v124
	v_cvt_pk_bf16_f32 v70, v70, s0
	global_store_short v[68:69], v70, off offset:3456
	s_mov_b64 s[4:5], 0

.LBB0_896:
	v_or_b32_e32 v34, v125, v171
	v_lshlrev_b32_e32 v35, 6, v34
	global_load_dwordx4 v[36:39], v35, s[44:45] offset:48
	global_load_dwordx4 v[40:43], v35, s[44:45] offset:32
	global_load_dwordx4 v[44:47], v35, s[44:45] offset:16
	global_load_dwordx4 v[48:51], v35, s[44:45]
	s_movk_i32 s4, 0x1fff
	v_bitop3_b32 v71, v125, s4, v171 bitop3:0xc8
	s_mov_b64 s[4:5], -1
	s_waitcnt vmcnt(2)
	v_add_f32_e32 v40, v40, v41
	v_add_f32_e32 v42, v42, v43
	s_waitcnt vmcnt(0)
	v_mov_b32_e32 v52, v49
	v_mov_b32_e32 v53, v50
	v_mov_b32_e32 v49, v51
	v_mov_b32_e32 v50, v45
	v_mov_b32_e32 v51, v46
	v_mov_b32_e32 v45, v47
	v_pk_add_f32 v[48:49], v[52:53], v[48:49]
	v_pk_add_f32 v[44:45], v[50:51], v[44:45]
	v_pk_add_f32 v[48:49], v[48:49], v[48:49] op_sel:[0,1] op_sel_hi:[1,0]
	v_pk_add_f32 v[44:45], v[44:45], v[44:45] op_sel:[0,1] op_sel_hi:[1,0]
	v_mov_b32_e32 v49, v36
	v_mov_b32_e32 v45, v37
	v_mov_b32_e32 v41, v38
	v_mov_b32_e32 v43, v39
	v_pk_add_f32 v[36:37], v[48:49], v[44:45]
	v_pk_add_f32 v[38:39], v[40:41], v[42:43]
	s_nop 0
	v_pk_add_f32 v[36:37], v[36:37], v[38:39]
	s_nop 0
	v_add_f32_e32 v35, v36, v37
	v_fmamk_f32 v35, v35, 0x3a800000, v174
	v_cmp_gt_f32_e32 vcc, s17, v35
	v_mul_f32_e32 v36, 0x4b800000, v35
	s_nop 0
	v_cndmask_b32_e32 v35, v35, v36, vcc
	v_rsq_f32_e32 v35, v35
	s_nop 0
	v_mul_f32_e32 v36, 0x45800000, v35
	v_cndmask_b32_e32 v70, v35, v36, vcc
	s_andn2_b64 vcc, exec, s[70:71]
	s_cbranch_vccnz .LBB0_902
	s_cmp_lt_i32 s66, 3
	s_cbranch_scc1 .LBB0_905
	s_cmp_gt_i32 s66, 3
	s_cbranch_scc0 .LBB0_903
	s_cmp_lg_u32 s66, 4
	s_cbranch_scc0 .LBB0_901
	v_readlane_b32 s4, v231, 28
	v_readlane_b32 s5, v231, 29
	v_lshlrev_b32_e32 v35, 7, v71
	v_and_b32_e32 v38, 0xfe000, v35
	v_lshl_add_u64 v[36:37], s[4:5], 0, v[98:99]
	v_mov_b32_e32 v39, v99
	v_lshl_add_u64 v[36:37], v[36:37], 0, v[38:39]
	v_lshlrev_b32_e32 v38, 1, v215
	v_lshl_add_u64 v[36:37], v[36:37], 0, v[38:39]
	v_mul_f32_e32 v35, v18, v70
	v_lshlrev_b32_e32 v38, 1, v102
	v_cvt_pk_bf16_f32 v35, v35, s0
	v_lshl_add_u64 v[36:37], v[36:37], 0, v[38:39]
	global_store_short v[36:37], v35, off
	v_mul_f32_e32 v35, v19, v70
	v_cvt_pk_bf16_f32 v35, v35, s0
	global_store_short v[36:37], v35, off offset:128
	v_mul_f32_e32 v35, v20, v70
	v_cvt_pk_bf16_f32 v35, v35, s0
	global_store_short v[36:37], v35, off offset:256
	v_mul_f32_e32 v35, v21, v70
	v_cvt_pk_bf16_f32 v35, v35, s0
	global_store_short v[36:37], v35, off offset:384
	v_mul_f32_e32 v35, v22, v70
	v_cvt_pk_bf16_f32 v35, v35, s0
	global_store_short v[36:37], v35, off offset:1024
	v_mul_f32_e32 v35, v23, v70
	v_cvt_pk_bf16_f32 v35, v35, s0
	global_store_short v[36:37], v35, off offset:1152
	v_mul_f32_e32 v35, v24, v70
	v_cvt_pk_bf16_f32 v35, v35, s0
	global_store_short v[36:37], v35, off offset:1280
	v_mul_f32_e32 v35, v25, v70
	v_cvt_pk_bf16_f32 v35, v35, s0
	global_store_short v[36:37], v35, off offset:1408
	v_mul_f32_e32 v35, v26, v70
	v_cvt_pk_bf16_f32 v35, v35, s0
	global_store_short v[36:37], v35, off offset:2048
	v_mul_f32_e32 v35, v27, v70
	v_cvt_pk_bf16_f32 v35, v35, s0
	global_store_short v[36:37], v35, off offset:2176
	v_mul_f32_e32 v35, v28, v70
	v_cvt_pk_bf16_f32 v35, v35, s0
	global_store_short v[36:37], v35, off offset:2304
	v_mul_f32_e32 v35, v29, v70
	v_cvt_pk_bf16_f32 v35, v35, s0
	global_store_short v[36:37], v35, off offset:2432
	v_mul_f32_e32 v35, v30, v70
	v_cvt_pk_bf16_f32 v35, v35, s0
	global_store_short v[36:37], v35, off offset:3072
	v_mul_f32_e32 v35, v31, v70
	v_cvt_pk_bf16_f32 v35, v35, s0
	global_store_short v[36:37], v35, off offset:3200
	v_mul_f32_e32 v35, v32, v70
	v_cvt_pk_bf16_f32 v35, v35, s0
	global_store_short v[36:37], v35, off offset:3328
	v_mul_f32_e32 v35, v33, v70
	v_cvt_pk_bf16_f32 v35, v35, s0
	global_store_short v[36:37], v35, off offset:3456
	v_mul_f32_e32 v35, v2, v70
	v_add_co_u32_e32 v36, vcc, s13, v36
	v_cvt_pk_bf16_f32 v35, v35, s0
	s_nop 0
	v_addc_co_u32_e32 v37, vcc, 0, v37, vcc
	global_store_short v[36:37], v35, off
	v_mul_f32_e32 v35, v3, v70
	v_cvt_pk_bf16_f32 v35, v35, s0
	global_store_short v[36:37], v35, off offset:128
	v_mul_f32_e32 v35, v4, v70
	v_cvt_pk_bf16_f32 v35, v35, s0
	global_store_short v[36:37], v35, off offset:256
	v_mul_f32_e32 v35, v5, v70
	v_cvt_pk_bf16_f32 v35, v35, s0
	global_store_short v[36:37], v35, off offset:384
	v_mul_f32_e32 v35, v6, v70
	v_cvt_pk_bf16_f32 v35, v35, s0
	global_store_short v[36:37], v35, off offset:1024
	v_mul_f32_e32 v35, v7, v70
	v_cvt_pk_bf16_f32 v35, v35, s0
	global_store_short v[36:37], v35, off offset:1152
	v_mul_f32_e32 v35, v8, v70
	v_cvt_pk_bf16_f32 v35, v35, s0
	global_store_short v[36:37], v35, off offset:1280
	v_mul_f32_e32 v35, v9, v70
	v_cvt_pk_bf16_f32 v35, v35, s0
	global_store_short v[36:37], v35, off offset:1408
	v_mul_f32_e32 v35, v10, v70
	v_cvt_pk_bf16_f32 v35, v35, s0
	global_store_short v[36:37], v35, off offset:2048
	v_mul_f32_e32 v35, v11, v70
	v_cvt_pk_bf16_f32 v35, v35, s0
	global_store_short v[36:37], v35, off offset:2176
	v_mul_f32_e32 v35, v12, v70
	v_cvt_pk_bf16_f32 v35, v35, s0
	global_store_short v[36:37], v35, off offset:2304
	v_mul_f32_e32 v35, v13, v70
	v_cvt_pk_bf16_f32 v35, v35, s0
	global_store_short v[36:37], v35, off offset:2432
	v_mul_f32_e32 v35, v14, v70
	v_cvt_pk_bf16_f32 v35, v35, s0
	global_store_short v[36:37], v35, off offset:3072
	v_mul_f32_e32 v35, v15, v70
	v_cvt_pk_bf16_f32 v35, v35, s0
	global_store_short v[36:37], v35, off offset:3200
	v_mul_f32_e32 v35, v16, v70
	v_cvt_pk_bf16_f32 v35, v35, s0
	global_store_short v[36:37], v35, off offset:3328
	v_mul_f32_e32 v35, v17, v70
	v_cvt_pk_bf16_f32 v35, v35, s0
	global_store_short v[36:37], v35, off offset:3456
	s_mov_b64 s[4:5], 0

.LBB0_2180:
	v_add_u32_e32 v46, s96, v236
	v_mov_b32_e32 v47, 0xc0
	v_mad_u64_u32 v[34:35], s[98:99], v46, v47, v[124:125]
	v_and_b32_e32 v48, 7, v166
	v_or_b32_e32 v48, s95, v48
	v_lshlrev_b32_e32 v48, 2, v48
	v_mov_b32_e32 v49, 0
	v_lshl_add_u64 v[34:35], v[34:35], 0, v[48:49]
	global_load_dword v133, v[34:35], off offset:128
	global_load_dword v148, v[34:35], off offset:512
	s_sub_i32 s20, 0x1df1, s70
	s_max_i32 s20, s20, 0
	s_lshr_b32 s59, s20, 6
	s_sub_i32 s101, s72, s59
	s_add_i32 s101, s101, 1
	s_lshl_b32 s22, s24, 1
	v_readlane_b32 s20, v231, 26
	s_add_u32 s20, s20, s22
	v_readlane_b32 s21, v231, 27
	s_addc_u32 s21, s21, 0
	v_readlane_b32 s28, v231, 28
	v_readlane_b32 s29, v231, 29
	s_add_u32 s22, s28, s22
	s_addc_u32 s23, s29, 0
	s_mov_b32 s25, 0
	s_add_i32 s32, s59, s25
	s_lshl_b32 s32, s32, 13
	s_add_u32 s28, s20, s32
	s_addc_u32 s29, s21, 0
	s_add_u32 s82, s22, s32
	s_addc_u32 s83, s23, 0
	global_load_dwordx4 v[240:243], v134, s[28:29]
	global_load_dwordx4 v[244:247], v134, s[82:83]
	global_load_dwordx4 v[248:251], v135, s[28:29]
	global_load_dwordx4 v[252:255], v135, s[82:83]
	s_cmp_lt_u32 s101, 2
	s_cbranch_scc1 .Lsb16_wpa
	s_mov_b32 s58, 1
	s_add_i32 s32, s59, s58
	s_lshl_b32 s32, s32, 13
	s_add_u32 s28, s20, s32
	s_addc_u32 s29, s21, 0
	s_add_u32 s82, s22, s32
	s_addc_u32 s83, s23, 0
	global_load_dwordx4 v[82:85], v134, s[28:29]
	global_load_dwordx4 v[86:89], v134, s[82:83]
	global_load_dwordx4 v[90:93], v135, s[28:29]
	global_load_dwordx4 v[94:97], v135, s[82:83]
.Lsb16_wpa:
	v_mbcnt_lo_u32_b32 v40, -1, 0
	v_mbcnt_hi_u32_b32 v40, -1, v40
	v_xor_b32_e32 v41, 16, v40
	v_lshlrev_b32_e32 v41, 2, v41
	v_xor_b32_e32 v42, 32, v40
	v_lshlrev_b32_e32 v42, 2, v42
	ds_bpermute_b32 v43, v41, v129
	ds_bpermute_b32 v44, v41, v235
	s_waitcnt lgkmcnt(0)
	v_add_f32_e32 v129, v129, v43
	v_add_f32_e32 v235, v235, v44
	s_nop 0
	ds_bpermute_b32 v43, v42, v129
	ds_bpermute_b32 v44, v42, v235
	s_waitcnt lgkmcnt(0)
	v_add_f32_e32 v129, v129, v43
	v_add_f32_e32 v235, v235, v44
	v_div_scale_f32 v40, s[98:99], v129, v129, v149
	v_rcp_f32_e32 v41, v40
	v_div_scale_f32 v42, vcc, v149, v129, v149
	v_fma_f32 v43, -v40, v41, 1.0
	v_fmac_f32_e32 v41, v43, v41
	v_mul_f32_e32 v43, v42, v41
	v_fma_f32 v38, -v40, v43, v42
	v_fmac_f32_e32 v43, v38, v41
	v_fma_f32 v40, -v40, v43, v42
	v_div_fmas_f32 v40, v40, v41, v43
	v_div_fixup_f32 v38, v40, v129, v149
	v_div_scale_f32 v40, s[98:99], v235, v235, v147
	v_rcp_f32_e32 v41, v40
	v_div_scale_f32 v42, vcc, v147, v235, v147
	v_fma_f32 v43, -v40, v41, 1.0
	v_fmac_f32_e32 v41, v43, v41
	v_mul_f32_e32 v43, v42, v41
	v_fma_f32 v44, -v40, v43, v42
	v_fmac_f32_e32 v43, v44, v41
	v_fma_f32 v40, -v40, v43, v42
	v_div_fmas_f32 v40, v40, v41, v43
	v_div_fixup_f32 v44, v40, v235, v147
	ds_read2_b32 v[50:51], v237 offset0:0 offset1:1
	ds_read2_b32 v[52:53], v237 offset0:2 offset1:3
	ds_read2_b32 v[54:55], v237 offset0:16 offset1:17
	ds_read2_b32 v[56:57], v237 offset0:18 offset1:19
	ds_read2_b32 v[58:59], v237 offset0:32 offset1:33
	ds_read2_b32 v[60:61], v237 offset0:34 offset1:35
	ds_read2_b32 v[62:63], v237 offset0:48 offset1:49
	ds_read2_b32 v[64:65], v237 offset0:50 offset1:51
	s_waitcnt lgkmcnt(7)
	v_pk_fma_f32 v[50:51], v[2:3], v[38:39], v[50:51] op_sel_hi:[1,0,1]
	s_waitcnt lgkmcnt(6)
	v_pk_fma_f32 v[52:53], v[4:5], v[38:39], v[52:53] op_sel_hi:[1,0,1]
	s_waitcnt lgkmcnt(5)
	v_pk_fma_f32 v[54:55], v[6:7], v[38:39], v[54:55] op_sel_hi:[1,0,1]
	s_waitcnt lgkmcnt(4)
	v_pk_fma_f32 v[56:57], v[8:9], v[38:39], v[56:57] op_sel_hi:[1,0,1]
	s_waitcnt lgkmcnt(3)
	v_pk_fma_f32 v[58:59], v[10:11], v[38:39], v[58:59] op_sel_hi:[1,0,1]
	s_waitcnt lgkmcnt(2)
	v_pk_fma_f32 v[60:61], v[12:13], v[38:39], v[60:61] op_sel_hi:[1,0,1]
	s_waitcnt lgkmcnt(1)
	v_pk_fma_f32 v[62:63], v[14:15], v[38:39], v[62:63] op_sel_hi:[1,0,1]
	s_waitcnt lgkmcnt(0)
	v_pk_fma_f32 v[64:65], v[16:17], v[38:39], v[64:65] op_sel_hi:[1,0,1]
	ds_write2_b32 v237, v50, v51 offset0:0 offset1:1
	ds_write2_b32 v237, v52, v53 offset0:2 offset1:3
	ds_write2_b32 v237, v54, v55 offset0:16 offset1:17
	ds_write2_b32 v237, v56, v57 offset0:18 offset1:19
	ds_write2_b32 v237, v58, v59 offset0:32 offset1:33
	ds_write2_b32 v237, v60, v61 offset0:34 offset1:35
	ds_write2_b32 v237, v62, v63 offset0:48 offset1:49
	ds_write2_b32 v237, v64, v65 offset0:50 offset1:51
	ds_read2_b32 v[50:51], v238 offset0:0 offset1:1
	ds_read2_b32 v[52:53], v238 offset0:2 offset1:3
	ds_read2_b32 v[54:55], v238 offset0:16 offset1:17
	ds_read2_b32 v[56:57], v238 offset0:18 offset1:19
	ds_read2_b32 v[58:59], v238 offset0:32 offset1:33
	ds_read2_b32 v[60:61], v238 offset0:34 offset1:35
	ds_read2_b32 v[62:63], v238 offset0:48 offset1:49
	ds_read2_b32 v[64:65], v238 offset0:50 offset1:51
	s_waitcnt lgkmcnt(7)
	v_pk_fma_f32 v[50:51], v[18:19], v[44:45], v[50:51] op_sel_hi:[1,0,1]
	s_waitcnt lgkmcnt(6)
	v_pk_fma_f32 v[52:53], v[20:21], v[44:45], v[52:53] op_sel_hi:[1,0,1]
	s_waitcnt lgkmcnt(5)
	v_pk_fma_f32 v[54:55], v[22:23], v[44:45], v[54:55] op_sel_hi:[1,0,1]
	s_waitcnt lgkmcnt(4)
	v_pk_fma_f32 v[56:57], v[24:25], v[44:45], v[56:57] op_sel_hi:[1,0,1]
	s_waitcnt lgkmcnt(3)
	v_pk_fma_f32 v[58:59], v[26:27], v[44:45], v[58:59] op_sel_hi:[1,0,1]
	s_waitcnt lgkmcnt(2)
	v_pk_fma_f32 v[60:61], v[28:29], v[44:45], v[60:61] op_sel_hi:[1,0,1]
	s_waitcnt lgkmcnt(1)
	v_pk_fma_f32 v[62:63], v[30:31], v[44:45], v[62:63] op_sel_hi:[1,0,1]
	s_waitcnt lgkmcnt(0)
	v_pk_fma_f32 v[64:65], v[32:33], v[44:45], v[64:65] op_sel_hi:[1,0,1]
	ds_write2_b32 v238, v50, v51 offset0:0 offset1:1
	ds_write2_b32 v238, v52, v53 offset0:2 offset1:3
	ds_write2_b32 v238, v54, v55 offset0:16 offset1:17
	ds_write2_b32 v238, v56, v57 offset0:18 offset1:19
	ds_write2_b32 v238, v58, v59 offset0:32 offset1:33
	ds_write2_b32 v238, v60, v61 offset0:34 offset1:35
	ds_write2_b32 v238, v62, v63 offset0:48 offset1:49
	ds_write2_b32 v238, v64, v65 offset0:50 offset1:51
	v_mov_b32_e32 v2, 0
	v_mov_b32_e32 v3, 0
	v_mov_b32_e32 v4, 0
	v_mov_b32_e32 v5, 0
	v_mov_b32_e32 v6, 0
	v_mov_b32_e32 v7, 0
	v_mov_b32_e32 v8, 0
	v_mov_b32_e32 v9, 0
	v_mov_b32_e32 v10, 0
	v_mov_b32_e32 v11, 0
	v_mov_b32_e32 v12, 0
	v_mov_b32_e32 v13, 0
	v_mov_b32_e32 v14, 0
	v_mov_b32_e32 v15, 0
	v_mov_b32_e32 v16, 0
	v_mov_b32_e32 v17, 0
	v_mov_b32_e32 v18, 0
	v_mov_b32_e32 v19, 0
	v_mov_b32_e32 v20, 0
	v_mov_b32_e32 v21, 0
	v_mov_b32_e32 v22, 0
	v_mov_b32_e32 v23, 0
	v_mov_b32_e32 v24, 0
	v_mov_b32_e32 v25, 0
	v_mov_b32_e32 v26, 0
	v_mov_b32_e32 v27, 0
	v_mov_b32_e32 v28, 0
	v_mov_b32_e32 v29, 0
	v_mov_b32_e32 v30, 0
	v_mov_b32_e32 v31, 0
	v_mov_b32_e32 v32, 0
	v_mov_b32_e32 v33, 0
	v_mov_b32_e32 v129, 0
	v_mov_b32_e32 v235, 0
	s_cmp_lt_u32 s101, 2
	s_cbranch_scc1 .Lsb16_wpb
	s_waitcnt vmcnt(4)
	s_branch .Lsb16_wpc

.Lsb16_wpc:
	ds_write_b128 v153, v[240:243]
	ds_write_b128 v153, v[244:247] offset:9216
	ds_write_b128 v155, v[248:251]
	ds_write_b128 v155, v[252:255] offset:9216
	s_cmp_lt_u32 s101, 3
	s_cbranch_scc1 .Lsb16_wpd
	s_mov_b32 s58, 2
	s_add_i32 s32, s59, s58
	s_lshl_b32 s32, s32, 13
	s_add_u32 s28, s20, s32
	s_addc_u32 s29, s21, 0
	s_add_u32 s82, s22, s32
	s_addc_u32 s83, s23, 0
	global_load_dwordx4 v[240:243], v134, s[28:29]
	global_load_dwordx4 v[244:247], v134, s[82:83]
	global_load_dwordx4 v[248:251], v135, s[28:29]
	global_load_dwordx4 v[252:255], v135, s[82:83]
.Lsb16_wpd:
	s_waitcnt lgkmcnt(0)
	s_barrier
.Lsb16_wstep_0:
	ds_read_b128 v[50:53], v234
	ds_read_b128 v[54:57], v234 offset:64
	ds_read_b128 v[58:61], v234 offset:2304
	ds_read_b128 v[62:65], v234 offset:2368
	s_add_i32 s58, s25, 1
	s_cmp_ge_u32 s58, s101
	s_cbranch_scc1 .Lsb16_nost_w_0
	s_add_i32 s58, s25, 2
	s_cmp_ge_u32 s58, s101
	s_cbranch_scc1 .Lsb16_w0_w_0
	s_waitcnt vmcnt(4)
	s_branch .Lsb16_wr_w_0

.Lsb16_wr_w_0:
	ds_write_b128 v153, v[82:85] offset:18432
	ds_write_b128 v153, v[86:89] offset:27648
	ds_write_b128 v155, v[90:93] offset:18432
	ds_write_b128 v155, v[94:97] offset:27648
	s_add_i32 s58, s25, 3
	s_cmp_ge_u32 s58, s101
	s_cbranch_scc1 .Lsb16_done_w_0
	s_add_i32 s32, s59, s58
	s_lshl_b32 s32, s32, 13
	s_add_u32 s28, s20, s32
	s_addc_u32 s29, s21, 0
	s_add_u32 s82, s22, s32
	s_addc_u32 s83, s23, 0
	global_load_dwordx4 v[82:85], v134, s[28:29]
	global_load_dwordx4 v[86:89], v134, s[82:83]
	global_load_dwordx4 v[90:93], v135, s[28:29]
	global_load_dwordx4 v[94:97], v135, s[82:83]
	s_branch .Lsb16_done_w_0

.Lsb16_done_w_0:
	s_cmp_eq_u32 s25, 0
	s_cbranch_scc1 .Lsb16_wm_0
	s_add_i32 s58, s25, 1
	s_cmp_eq_u32 s58, s101
	s_cbranch_scc1 .Lsb16_wm_0
	s_waitcnt lgkmcnt(7)
	v_mfma_f32_16x16x32_bf16 v[34:37], v[50:53], v[66:69], 0
	v_mfma_f32_16x16x32_bf16 v[42:45], v[50:53], v[74:77], 0
	s_waitcnt lgkmcnt(6)
	v_mfma_f32_16x16x32_bf16 v[34:37], v[54:57], v[70:73], v[34:37]
	v_mfma_f32_16x16x32_bf16 v[42:45], v[54:57], v[78:81], v[42:45]
	s_waitcnt lgkmcnt(5)
	v_mfma_f32_16x16x32_bf16 v[38:41], v[58:61], v[66:69], 0
	v_mfma_f32_16x16x32_bf16 v[46:49], v[58:61], v[74:77], 0
	s_waitcnt lgkmcnt(4)
	v_mfma_f32_16x16x32_bf16 v[38:41], v[62:65], v[70:73], v[38:41]
	v_mfma_f32_16x16x32_bf16 v[46:49], v[62:65], v[78:81], v[46:49]
	ds_read_b128 v[50:53], v234 offset:9216
	ds_read_b128 v[54:57], v234 offset:11520
	ds_read_b128 v[58:61], v234 offset:13824
	ds_read_b128 v[62:65], v234 offset:16128
	v_fma_f32 v34, v34, s48, v100
	v_fma_f32 v35, v35, s48, v100
	v_fma_f32 v36, v36, s48, v100
	v_fma_f32 v37, v37, s48, v100
	v_fma_f32 v38, v38, s48, v100
	v_fma_f32 v39, v39, s48, v100
	v_fma_f32 v40, v40, s48, v100
	v_fma_f32 v41, v41, s48, v100
	v_fma_f32 v42, v42, s48, v100
	v_fma_f32 v43, v43, s48, v100
	v_fma_f32 v44, v44, s48, v100
	v_fma_f32 v45, v45, s48, v100
	v_fma_f32 v46, v46, s48, v100
	v_fma_f32 v47, v47, s48, v100
	v_fma_f32 v48, v48, s48, v100
	v_fma_f32 v49, v49, s48, v100
	v_exp_f32_e32 v34, v34
	v_exp_f32_e32 v35, v35
	v_exp_f32_e32 v36, v36
	v_exp_f32_e32 v37, v37
	v_exp_f32_e32 v38, v38
	v_exp_f32_e32 v39, v39
	v_exp_f32_e32 v40, v40
	v_exp_f32_e32 v41, v41
	v_exp_f32_e32 v42, v42
	v_exp_f32_e32 v43, v43
	v_exp_f32_e32 v44, v44
	v_exp_f32_e32 v45, v45
	v_exp_f32_e32 v46, v46
	v_exp_f32_e32 v47, v47
	v_exp_f32_e32 v48, v48
	v_exp_f32_e32 v49, v49
	v_add_f32_e32 v138, v34, v35
	v_add_f32_e32 v139, v36, v37
	v_add_f32_e32 v138, v138, v38
	v_add_f32_e32 v139, v139, v39
	v_add_f32_e32 v138, v138, v40
	v_add_f32_e32 v139, v139, v41
	v_add_f32_e32 v138, v138, v139
	v_add_f32_e32 v129, v129, v138
	v_add_f32_e32 v140, v42, v43
	v_add_f32_e32 v141, v44, v45
	v_add_f32_e32 v140, v140, v46
	v_add_f32_e32 v141, v141, v47
	v_add_f32_e32 v140, v140, v48
	v_add_f32_e32 v141, v141, v49
	v_add_f32_e32 v140, v140, v141
	v_add_f32_e32 v235, v235, v140
	v_cvt_pk_bf16_f32 v138, v34, v35
	v_cvt_pk_bf16_f32 v139, v36, v37
	v_cvt_pk_bf16_f32 v140, v38, v39
	v_cvt_pk_bf16_f32 v141, v40, v41
	v_cvt_pk_bf16_f32 v142, v42, v43
	v_cvt_pk_bf16_f32 v143, v44, v45
	v_cvt_pk_bf16_f32 v144, v46, v47
	v_cvt_pk_bf16_f32 v145, v48, v49
	s_waitcnt lgkmcnt(3)
	v_mfma_f32_16x16x32_bf16 v[2:5], v[50:53], v[138:141], v[2:5]
	v_mfma_f32_16x16x32_bf16 v[18:21], v[50:53], v[142:145], v[18:21]
	ds_read_b128 v[50:53], v234 offset:4608
	s_waitcnt lgkmcnt(3)
	v_mfma_f32_16x16x32_bf16 v[6:9], v[54:57], v[138:141], v[6:9]
	v_mfma_f32_16x16x32_bf16 v[22:25], v[54:57], v[142:145], v[22:25]
	ds_read_b128 v[54:57], v234 offset:4672
	s_waitcnt lgkmcnt(3)
	v_mfma_f32_16x16x32_bf16 v[10:13], v[58:61], v[138:141], v[10:13]
	v_mfma_f32_16x16x32_bf16 v[26:29], v[58:61], v[142:145], v[26:29]
	ds_read_b128 v[58:61], v234 offset:6912
	s_waitcnt lgkmcnt(3)
	v_mfma_f32_16x16x32_bf16 v[14:17], v[62:65], v[138:141], v[14:17]
	v_mfma_f32_16x16x32_bf16 v[30:33], v[62:65], v[142:145], v[30:33]
	ds_read_b128 v[62:65], v234 offset:6976
	s_waitcnt lgkmcnt(3)
	v_mfma_f32_16x16x32_bf16 v[34:37], v[50:53], v[66:69], 0
	v_mfma_f32_16x16x32_bf16 v[42:45], v[50:53], v[74:77], 0
	s_waitcnt lgkmcnt(2)
	v_mfma_f32_16x16x32_bf16 v[34:37], v[54:57], v[70:73], v[34:37]
	v_mfma_f32_16x16x32_bf16 v[42:45], v[54:57], v[78:81], v[42:45]
	s_waitcnt lgkmcnt(1)
	v_mfma_f32_16x16x32_bf16 v[38:41], v[58:61], v[66:69], 0
	v_mfma_f32_16x16x32_bf16 v[46:49], v[58:61], v[74:77], 0
	s_waitcnt lgkmcnt(0)
	v_mfma_f32_16x16x32_bf16 v[38:41], v[62:65], v[70:73], v[38:41]
	v_mfma_f32_16x16x32_bf16 v[46:49], v[62:65], v[78:81], v[46:49]
	ds_read_b128 v[50:53], v234 offset:9280
	ds_read_b128 v[54:57], v234 offset:11584
	ds_read_b128 v[58:61], v234 offset:13888
	ds_read_b128 v[62:65], v234 offset:16192
	v_fma_f32 v34, v34, s48, v100
	v_fma_f32 v35, v35, s48, v100
	v_fma_f32 v36, v36, s48, v100
	v_fma_f32 v37, v37, s48, v100
	v_fma_f32 v38, v38, s48, v100
	v_fma_f32 v39, v39, s48, v100
	v_fma_f32 v40, v40, s48, v100
	v_fma_f32 v41, v41, s48, v100
	v_fma_f32 v42, v42, s48, v100
	v_fma_f32 v43, v43, s48, v100
	v_fma_f32 v44, v44, s48, v100
	v_fma_f32 v45, v45, s48, v100
	v_fma_f32 v46, v46, s48, v100
	v_fma_f32 v47, v47, s48, v100
	v_fma_f32 v48, v48, s48, v100
	v_fma_f32 v49, v49, s48, v100
	v_exp_f32_e32 v34, v34
	v_exp_f32_e32 v35, v35
	v_exp_f32_e32 v36, v36
	v_exp_f32_e32 v37, v37
	v_exp_f32_e32 v38, v38
	v_exp_f32_e32 v39, v39
	v_exp_f32_e32 v40, v40
	v_exp_f32_e32 v41, v41
	v_exp_f32_e32 v42, v42
	v_exp_f32_e32 v43, v43
	v_exp_f32_e32 v44, v44
	v_exp_f32_e32 v45, v45
	v_exp_f32_e32 v46, v46
	v_exp_f32_e32 v47, v47
	v_exp_f32_e32 v48, v48
	v_exp_f32_e32 v49, v49
	v_add_f32_e32 v138, v34, v35
	v_add_f32_e32 v139, v36, v37
	v_add_f32_e32 v138, v138, v38
	v_add_f32_e32 v139, v139, v39
	v_add_f32_e32 v138, v138, v40
	v_add_f32_e32 v139, v139, v41
	v_add_f32_e32 v138, v138, v139
	v_add_f32_e32 v129, v129, v138
	v_add_f32_e32 v140, v42, v43
	v_add_f32_e32 v141, v44, v45
	v_add_f32_e32 v140, v140, v46
	v_add_f32_e32 v141, v141, v47
	v_add_f32_e32 v140, v140, v48
	v_add_f32_e32 v141, v141, v49
	v_add_f32_e32 v140, v140, v141
	v_add_f32_e32 v235, v235, v140
	v_cvt_pk_bf16_f32 v138, v34, v35
	v_cvt_pk_bf16_f32 v139, v36, v37
	v_cvt_pk_bf16_f32 v140, v38, v39
	v_cvt_pk_bf16_f32 v141, v40, v41
	v_cvt_pk_bf16_f32 v142, v42, v43
	v_cvt_pk_bf16_f32 v143, v44, v45
	v_cvt_pk_bf16_f32 v144, v46, v47
	v_cvt_pk_bf16_f32 v145, v48, v49
	s_waitcnt lgkmcnt(3)
	v_mfma_f32_16x16x32_bf16 v[2:5], v[50:53], v[138:141], v[2:5]
	v_mfma_f32_16x16x32_bf16 v[18:21], v[50:53], v[142:145], v[18:21]
	s_waitcnt lgkmcnt(2)
	v_mfma_f32_16x16x32_bf16 v[6:9], v[54:57], v[138:141], v[6:9]
	v_mfma_f32_16x16x32_bf16 v[22:25], v[54:57], v[142:145], v[22:25]
	s_waitcnt lgkmcnt(1)
	v_mfma_f32_16x16x32_bf16 v[10:13], v[58:61], v[138:141], v[10:13]
	v_mfma_f32_16x16x32_bf16 v[26:29], v[58:61], v[142:145], v[26:29]
	s_waitcnt lgkmcnt(0)
	v_mfma_f32_16x16x32_bf16 v[14:17], v[62:65], v[138:141], v[14:17]
	v_mfma_f32_16x16x32_bf16 v[30:33], v[62:65], v[142:145], v[30:33]
	s_branch .Lsb16_wend_0
.Lsb16_wm_0:
	s_add_i32 s83, s59, s25
	s_lshl_b32 s83, s83, 6
	s_movk_i32 s58, 0x1ff
	s_waitcnt lgkmcnt(7)
	v_mfma_f32_16x16x32_bf16 v[34:37], v[50:53], v[66:69], 0
	v_mfma_f32_16x16x32_bf16 v[42:45], v[50:53], v[74:77], 0
	s_waitcnt lgkmcnt(6)
	v_mfma_f32_16x16x32_bf16 v[34:37], v[54:57], v[70:73], v[34:37]
	v_mfma_f32_16x16x32_bf16 v[42:45], v[54:57], v[78:81], v[42:45]
	s_waitcnt lgkmcnt(5)
	v_mfma_f32_16x16x32_bf16 v[38:41], v[58:61], v[66:69], 0
	v_mfma_f32_16x16x32_bf16 v[46:49], v[58:61], v[74:77], 0
	s_waitcnt lgkmcnt(4)
	v_mfma_f32_16x16x32_bf16 v[38:41], v[62:65], v[70:73], v[38:41]
	v_mfma_f32_16x16x32_bf16 v[46:49], v[62:65], v[78:81], v[46:49]
	ds_read_b128 v[50:53], v234 offset:9216
	ds_read_b128 v[54:57], v234 offset:11520
	ds_read_b128 v[58:61], v234 offset:13824
	ds_read_b128 v[62:65], v234 offset:16128
	v_subrev_u32_e32 v146, s83, v239
	v_add_u32_e32 v145, 2, v146
	v_fma_f32 v34, v34, s48, v100
	v_fma_f32 v35, v35, s48, v100
	v_fma_f32 v36, v36, s48, v100
	v_fma_f32 v37, v37, s48, v100
	v_fma_f32 v38, v38, s48, v100
	v_fma_f32 v39, v39, s48, v100
	v_fma_f32 v40, v40, s48, v100
	v_fma_f32 v41, v41, s48, v100
	v_fma_f32 v42, v42, s48, v100
	v_fma_f32 v43, v43, s48, v100
	v_fma_f32 v44, v44, s48, v100
	v_fma_f32 v45, v45, s48, v100
	v_fma_f32 v46, v46, s48, v100
	v_fma_f32 v47, v47, s48, v100
	v_fma_f32 v48, v48, s48, v100
	v_fma_f32 v49, v49, s48, v100
	v_subrev_u32_e32 v136, 0, v146
	v_subrev_u32_e32 v137, 1, v146
	v_cmp_ge_u32_e32 vcc, 0x1ff, v136
	v_cmp_ge_u32_e64 s[28:29], s58, v137
	s_nop 0
	v_cndmask_b32_e32 v34, v213, v34, vcc
	v_cndmask_b32_e64 v35, v213, v35, s[28:29]
	v_subrev_u32_e32 v136, 2, v146
	v_subrev_u32_e32 v137, 3, v146
	v_cmp_ge_u32_e32 vcc, 0x1ff, v136
	v_cmp_ge_u32_e64 s[28:29], s58, v137
	s_nop 0
	v_cndmask_b32_e32 v36, v213, v36, vcc
	v_cndmask_b32_e64 v37, v213, v37, s[28:29]
	v_subrev_u32_e32 v136, 16, v146
	v_subrev_u32_e32 v137, 17, v146
	v_cmp_ge_u32_e32 vcc, 0x1ff, v136
	v_cmp_ge_u32_e64 s[28:29], s58, v137
	s_nop 0
	v_cndmask_b32_e32 v38, v213, v38, vcc
	v_cndmask_b32_e64 v39, v213, v39, s[28:29]
	v_subrev_u32_e32 v136, 18, v146
	v_subrev_u32_e32 v137, 19, v146
	v_cmp_ge_u32_e32 vcc, 0x1ff, v136
	v_cmp_ge_u32_e64 s[28:29], s58, v137
	s_nop 0
	v_cndmask_b32_e32 v40, v213, v40, vcc
	v_cndmask_b32_e64 v41, v213, v41, s[28:29]
	v_subrev_u32_e32 v136, 0, v145
	v_subrev_u32_e32 v137, 1, v145
	v_cmp_ge_u32_e32 vcc, 0x1ff, v136
	v_cmp_ge_u32_e64 s[28:29], s58, v137
	s_nop 0
	v_cndmask_b32_e32 v42, v213, v42, vcc
	v_cndmask_b32_e64 v43, v213, v43, s[28:29]
	v_subrev_u32_e32 v136, 2, v145
	v_subrev_u32_e32 v137, 3, v145
	v_cmp_ge_u32_e32 vcc, 0x1ff, v136
	v_cmp_ge_u32_e64 s[28:29], s58, v137
	s_nop 0
	v_cndmask_b32_e32 v44, v213, v44, vcc
	v_cndmask_b32_e64 v45, v213, v45, s[28:29]
	v_subrev_u32_e32 v136, 16, v145
	v_subrev_u32_e32 v137, 17, v145
	v_cmp_ge_u32_e32 vcc, 0x1ff, v136
	v_cmp_ge_u32_e64 s[28:29], s58, v137
	s_nop 0
	v_cndmask_b32_e32 v46, v213, v46, vcc
	v_cndmask_b32_e64 v47, v213, v47, s[28:29]
	v_subrev_u32_e32 v136, 18, v145
	v_subrev_u32_e32 v137, 19, v145
	v_cmp_ge_u32_e32 vcc, 0x1ff, v136
	v_cmp_ge_u32_e64 s[28:29], s58, v137
	s_nop 0
	v_cndmask_b32_e32 v48, v213, v48, vcc
	v_cndmask_b32_e64 v49, v213, v49, s[28:29]
	v_exp_f32_e32 v34, v34
	v_exp_f32_e32 v35, v35
	v_exp_f32_e32 v36, v36
	v_exp_f32_e32 v37, v37
	v_exp_f32_e32 v38, v38
	v_exp_f32_e32 v39, v39
	v_exp_f32_e32 v40, v40
	v_exp_f32_e32 v41, v41
	v_exp_f32_e32 v42, v42
	v_exp_f32_e32 v43, v43
	v_exp_f32_e32 v44, v44
	v_exp_f32_e32 v45, v45
	v_exp_f32_e32 v46, v46
	v_exp_f32_e32 v47, v47
	v_exp_f32_e32 v48, v48
	v_exp_f32_e32 v49, v49
	v_add_f32_e32 v138, v34, v35
	v_add_f32_e32 v139, v36, v37
	v_add_f32_e32 v138, v138, v38
	v_add_f32_e32 v139, v139, v39
	v_add_f32_e32 v138, v138, v40
	v_add_f32_e32 v139, v139, v41
	v_add_f32_e32 v138, v138, v139
	v_add_f32_e32 v129, v129, v138
	v_add_f32_e32 v140, v42, v43
	v_add_f32_e32 v141, v44, v45
	v_add_f32_e32 v140, v140, v46
	v_add_f32_e32 v141, v141, v47
	v_add_f32_e32 v140, v140, v48
	v_add_f32_e32 v141, v141, v49
	v_add_f32_e32 v140, v140, v141
	v_add_f32_e32 v235, v235, v140
	v_cvt_pk_bf16_f32 v138, v34, v35
	v_cvt_pk_bf16_f32 v139, v36, v37
	v_cvt_pk_bf16_f32 v140, v38, v39
	v_cvt_pk_bf16_f32 v141, v40, v41
	v_cvt_pk_bf16_f32 v142, v42, v43
	v_cvt_pk_bf16_f32 v143, v44, v45
	v_cvt_pk_bf16_f32 v144, v46, v47
	v_cvt_pk_bf16_f32 v145, v48, v49
	s_waitcnt lgkmcnt(3)
	v_mfma_f32_16x16x32_bf16 v[2:5], v[50:53], v[138:141], v[2:5]
	v_mfma_f32_16x16x32_bf16 v[18:21], v[50:53], v[142:145], v[18:21]
	ds_read_b128 v[50:53], v234 offset:4608
	s_waitcnt lgkmcnt(3)
	v_mfma_f32_16x16x32_bf16 v[6:9], v[54:57], v[138:141], v[6:9]
	v_mfma_f32_16x16x32_bf16 v[22:25], v[54:57], v[142:145], v[22:25]
	ds_read_b128 v[54:57], v234 offset:4672
	s_waitcnt lgkmcnt(3)
	v_mfma_f32_16x16x32_bf16 v[10:13], v[58:61], v[138:141], v[10:13]
	v_mfma_f32_16x16x32_bf16 v[26:29], v[58:61], v[142:145], v[26:29]
	ds_read_b128 v[58:61], v234 offset:6912
	s_waitcnt lgkmcnt(3)
	v_mfma_f32_16x16x32_bf16 v[14:17], v[62:65], v[138:141], v[14:17]
	v_mfma_f32_16x16x32_bf16 v[30:33], v[62:65], v[142:145], v[30:33]
	ds_read_b128 v[62:65], v234 offset:6976
	s_waitcnt lgkmcnt(3)
	v_mfma_f32_16x16x32_bf16 v[34:37], v[50:53], v[66:69], 0
	v_mfma_f32_16x16x32_bf16 v[42:45], v[50:53], v[74:77], 0
	s_waitcnt lgkmcnt(2)
	v_mfma_f32_16x16x32_bf16 v[34:37], v[54:57], v[70:73], v[34:37]
	v_mfma_f32_16x16x32_bf16 v[42:45], v[54:57], v[78:81], v[42:45]
	s_waitcnt lgkmcnt(1)
	v_mfma_f32_16x16x32_bf16 v[38:41], v[58:61], v[66:69], 0
	v_mfma_f32_16x16x32_bf16 v[46:49], v[58:61], v[74:77], 0
	s_waitcnt lgkmcnt(0)
	v_mfma_f32_16x16x32_bf16 v[38:41], v[62:65], v[70:73], v[38:41]
	v_mfma_f32_16x16x32_bf16 v[46:49], v[62:65], v[78:81], v[46:49]
	ds_read_b128 v[50:53], v234 offset:9280
	ds_read_b128 v[54:57], v234 offset:11584
	ds_read_b128 v[58:61], v234 offset:13888
	ds_read_b128 v[62:65], v234 offset:16192
	v_subrev_u32_e32 v146, s83, v239
	v_add_u32_e32 v145, 2, v146
	v_fma_f32 v34, v34, s48, v100
	v_fma_f32 v35, v35, s48, v100
	v_fma_f32 v36, v36, s48, v100
	v_fma_f32 v37, v37, s48, v100
	v_fma_f32 v38, v38, s48, v100
	v_fma_f32 v39, v39, s48, v100
	v_fma_f32 v40, v40, s48, v100
	v_fma_f32 v41, v41, s48, v100
	v_fma_f32 v42, v42, s48, v100
	v_fma_f32 v43, v43, s48, v100
	v_fma_f32 v44, v44, s48, v100
	v_fma_f32 v45, v45, s48, v100
	v_fma_f32 v46, v46, s48, v100
	v_fma_f32 v47, v47, s48, v100
	v_fma_f32 v48, v48, s48, v100
	v_fma_f32 v49, v49, s48, v100
	v_subrev_u32_e32 v136, 32, v146
	v_subrev_u32_e32 v137, 33, v146
	v_cmp_ge_u32_e32 vcc, 0x1ff, v136
	v_cmp_ge_u32_e64 s[28:29], s58, v137
	s_nop 0
	v_cndmask_b32_e32 v34, v213, v34, vcc
	v_cndmask_b32_e64 v35, v213, v35, s[28:29]
	v_subrev_u32_e32 v136, 34, v146
	v_subrev_u32_e32 v137, 35, v146
	v_cmp_ge_u32_e32 vcc, 0x1ff, v136
	v_cmp_ge_u32_e64 s[28:29], s58, v137
	s_nop 0
	v_cndmask_b32_e32 v36, v213, v36, vcc
	v_cndmask_b32_e64 v37, v213, v37, s[28:29]
	v_subrev_u32_e32 v136, 48, v146
	v_subrev_u32_e32 v137, 49, v146
	v_cmp_ge_u32_e32 vcc, 0x1ff, v136
	v_cmp_ge_u32_e64 s[28:29], s58, v137
	s_nop 0
	v_cndmask_b32_e32 v38, v213, v38, vcc
	v_cndmask_b32_e64 v39, v213, v39, s[28:29]
	v_subrev_u32_e32 v136, 50, v146
	v_subrev_u32_e32 v137, 51, v146
	v_cmp_ge_u32_e32 vcc, 0x1ff, v136
	v_cmp_ge_u32_e64 s[28:29], s58, v137
	s_nop 0
	v_cndmask_b32_e32 v40, v213, v40, vcc
	v_cndmask_b32_e64 v41, v213, v41, s[28:29]
	v_subrev_u32_e32 v136, 32, v145
	v_subrev_u32_e32 v137, 33, v145
	v_cmp_ge_u32_e32 vcc, 0x1ff, v136
	v_cmp_ge_u32_e64 s[28:29], s58, v137
	s_nop 0
	v_cndmask_b32_e32 v42, v213, v42, vcc
	v_cndmask_b32_e64 v43, v213, v43, s[28:29]
	v_subrev_u32_e32 v136, 34, v145
	v_subrev_u32_e32 v137, 35, v145
	v_cmp_ge_u32_e32 vcc, 0x1ff, v136
	v_cmp_ge_u32_e64 s[28:29], s58, v137
	s_nop 0
	v_cndmask_b32_e32 v44, v213, v44, vcc
	v_cndmask_b32_e64 v45, v213, v45, s[28:29]
	v_subrev_u32_e32 v136, 48, v145
	v_subrev_u32_e32 v137, 49, v145
	v_cmp_ge_u32_e32 vcc, 0x1ff, v136
	v_cmp_ge_u32_e64 s[28:29], s58, v137
	s_nop 0
	v_cndmask_b32_e32 v46, v213, v46, vcc
	v_cndmask_b32_e64 v47, v213, v47, s[28:29]
	v_subrev_u32_e32 v136, 50, v145
	v_subrev_u32_e32 v137, 51, v145
	v_cmp_ge_u32_e32 vcc, 0x1ff, v136
	v_cmp_ge_u32_e64 s[28:29], s58, v137
	s_nop 0
	v_cndmask_b32_e32 v48, v213, v48, vcc
	v_cndmask_b32_e64 v49, v213, v49, s[28:29]
	v_exp_f32_e32 v34, v34
	v_exp_f32_e32 v35, v35
	v_exp_f32_e32 v36, v36
	v_exp_f32_e32 v37, v37
	v_exp_f32_e32 v38, v38
	v_exp_f32_e32 v39, v39
	v_exp_f32_e32 v40, v40
	v_exp_f32_e32 v41, v41
	v_exp_f32_e32 v42, v42
	v_exp_f32_e32 v43, v43
	v_exp_f32_e32 v44, v44
	v_exp_f32_e32 v45, v45
	v_exp_f32_e32 v46, v46
	v_exp_f32_e32 v47, v47
	v_exp_f32_e32 v48, v48
	v_exp_f32_e32 v49, v49
	v_add_f32_e32 v138, v34, v35
	v_add_f32_e32 v139, v36, v37
	v_add_f32_e32 v138, v138, v38
	v_add_f32_e32 v139, v139, v39
	v_add_f32_e32 v138, v138, v40
	v_add_f32_e32 v139, v139, v41
	v_add_f32_e32 v138, v138, v139
	v_add_f32_e32 v129, v129, v138
	v_add_f32_e32 v140, v42, v43
	v_add_f32_e32 v141, v44, v45
	v_add_f32_e32 v140, v140, v46
	v_add_f32_e32 v141, v141, v47
	v_add_f32_e32 v140, v140, v48
	v_add_f32_e32 v141, v141, v49
	v_add_f32_e32 v140, v140, v141
	v_add_f32_e32 v235, v235, v140
	v_cvt_pk_bf16_f32 v138, v34, v35
	v_cvt_pk_bf16_f32 v139, v36, v37
	v_cvt_pk_bf16_f32 v140, v38, v39
	v_cvt_pk_bf16_f32 v141, v40, v41
	v_cvt_pk_bf16_f32 v142, v42, v43
	v_cvt_pk_bf16_f32 v143, v44, v45
	v_cvt_pk_bf16_f32 v144, v46, v47
	v_cvt_pk_bf16_f32 v145, v48, v49
	s_waitcnt lgkmcnt(3)
	v_mfma_f32_16x16x32_bf16 v[2:5], v[50:53], v[138:141], v[2:5]
	v_mfma_f32_16x16x32_bf16 v[18:21], v[50:53], v[142:145], v[18:21]
	s_waitcnt lgkmcnt(2)
	v_mfma_f32_16x16x32_bf16 v[6:9], v[54:57], v[138:141], v[6:9]
	v_mfma_f32_16x16x32_bf16 v[22:25], v[54:57], v[142:145], v[22:25]
	s_waitcnt lgkmcnt(1)
	v_mfma_f32_16x16x32_bf16 v[10:13], v[58:61], v[138:141], v[10:13]
	v_mfma_f32_16x16x32_bf16 v[26:29], v[58:61], v[142:145], v[26:29]
	s_waitcnt lgkmcnt(0)
	v_mfma_f32_16x16x32_bf16 v[14:17], v[62:65], v[138:141], v[14:17]
	v_mfma_f32_16x16x32_bf16 v[30:33], v[62:65], v[142:145], v[30:33]

.Lsb16_wstep_1:
	ds_read_b128 v[50:53], v234 offset:18432
	ds_read_b128 v[54:57], v234 offset:18496
	ds_read_b128 v[58:61], v234 offset:20736
	ds_read_b128 v[62:65], v234 offset:20800
	s_add_i32 s58, s25, 1
	s_cmp_ge_u32 s58, s101
	s_cbranch_scc1 .Lsb16_nost_w_1
	s_add_i32 s58, s25, 2
	s_cmp_ge_u32 s58, s101
	s_cbranch_scc1 .Lsb16_w0_w_1
	s_waitcnt vmcnt(4)
	s_branch .Lsb16_wr_w_1

.Lsb16_wr_w_1:
	ds_write_b128 v153, v[240:243]
	ds_write_b128 v153, v[244:247] offset:9216
	ds_write_b128 v155, v[248:251]
	ds_write_b128 v155, v[252:255] offset:9216
	s_add_i32 s58, s25, 3
	s_cmp_ge_u32 s58, s101
	s_cbranch_scc1 .Lsb16_done_w_1
	s_add_i32 s32, s59, s58
	s_lshl_b32 s32, s32, 13
	s_add_u32 s28, s20, s32
	s_addc_u32 s29, s21, 0
	s_add_u32 s82, s22, s32
	s_addc_u32 s83, s23, 0
	global_load_dwordx4 v[240:243], v134, s[28:29]
	global_load_dwordx4 v[244:247], v134, s[82:83]
	global_load_dwordx4 v[248:251], v135, s[28:29]
	global_load_dwordx4 v[252:255], v135, s[82:83]
	s_branch .Lsb16_done_w_1

.Lsb16_done_w_1:
	s_cmp_eq_u32 s25, 0
	s_cbranch_scc1 .Lsb16_wm_1
	s_add_i32 s58, s25, 1
	s_cmp_eq_u32 s58, s101
	s_cbranch_scc1 .Lsb16_wm_1
	s_waitcnt lgkmcnt(7)
	v_mfma_f32_16x16x32_bf16 v[34:37], v[50:53], v[66:69], 0
	v_mfma_f32_16x16x32_bf16 v[42:45], v[50:53], v[74:77], 0
	s_waitcnt lgkmcnt(6)
	v_mfma_f32_16x16x32_bf16 v[34:37], v[54:57], v[70:73], v[34:37]
	v_mfma_f32_16x16x32_bf16 v[42:45], v[54:57], v[78:81], v[42:45]
	s_waitcnt lgkmcnt(5)
	v_mfma_f32_16x16x32_bf16 v[38:41], v[58:61], v[66:69], 0
	v_mfma_f32_16x16x32_bf16 v[46:49], v[58:61], v[74:77], 0
	s_waitcnt lgkmcnt(4)
	v_mfma_f32_16x16x32_bf16 v[38:41], v[62:65], v[70:73], v[38:41]
	v_mfma_f32_16x16x32_bf16 v[46:49], v[62:65], v[78:81], v[46:49]
	ds_read_b128 v[50:53], v234 offset:27648
	ds_read_b128 v[54:57], v234 offset:29952
	ds_read_b128 v[58:61], v234 offset:32256
	ds_read_b128 v[62:65], v234 offset:34560
	v_fma_f32 v34, v34, s48, v100
	v_fma_f32 v35, v35, s48, v100
	v_fma_f32 v36, v36, s48, v100
	v_fma_f32 v37, v37, s48, v100
	v_fma_f32 v38, v38, s48, v100
	v_fma_f32 v39, v39, s48, v100
	v_fma_f32 v40, v40, s48, v100
	v_fma_f32 v41, v41, s48, v100
	v_fma_f32 v42, v42, s48, v100
	v_fma_f32 v43, v43, s48, v100
	v_fma_f32 v44, v44, s48, v100
	v_fma_f32 v45, v45, s48, v100
	v_fma_f32 v46, v46, s48, v100
	v_fma_f32 v47, v47, s48, v100
	v_fma_f32 v48, v48, s48, v100
	v_fma_f32 v49, v49, s48, v100
	v_exp_f32_e32 v34, v34
	v_exp_f32_e32 v35, v35
	v_exp_f32_e32 v36, v36
	v_exp_f32_e32 v37, v37
	v_exp_f32_e32 v38, v38
	v_exp_f32_e32 v39, v39
	v_exp_f32_e32 v40, v40
	v_exp_f32_e32 v41, v41
	v_exp_f32_e32 v42, v42
	v_exp_f32_e32 v43, v43
	v_exp_f32_e32 v44, v44
	v_exp_f32_e32 v45, v45
	v_exp_f32_e32 v46, v46
	v_exp_f32_e32 v47, v47
	v_exp_f32_e32 v48, v48
	v_exp_f32_e32 v49, v49
	v_add_f32_e32 v138, v34, v35
	v_add_f32_e32 v139, v36, v37
	v_add_f32_e32 v138, v138, v38
	v_add_f32_e32 v139, v139, v39
	v_add_f32_e32 v138, v138, v40
	v_add_f32_e32 v139, v139, v41
	v_add_f32_e32 v138, v138, v139
	v_add_f32_e32 v129, v129, v138
	v_add_f32_e32 v140, v42, v43
	v_add_f32_e32 v141, v44, v45
	v_add_f32_e32 v140, v140, v46
	v_add_f32_e32 v141, v141, v47
	v_add_f32_e32 v140, v140, v48
	v_add_f32_e32 v141, v141, v49
	v_add_f32_e32 v140, v140, v141
	v_add_f32_e32 v235, v235, v140
	v_cvt_pk_bf16_f32 v138, v34, v35
	v_cvt_pk_bf16_f32 v139, v36, v37
	v_cvt_pk_bf16_f32 v140, v38, v39
	v_cvt_pk_bf16_f32 v141, v40, v41
	v_cvt_pk_bf16_f32 v142, v42, v43
	v_cvt_pk_bf16_f32 v143, v44, v45
	v_cvt_pk_bf16_f32 v144, v46, v47
	v_cvt_pk_bf16_f32 v145, v48, v49
	s_waitcnt lgkmcnt(3)
	v_mfma_f32_16x16x32_bf16 v[2:5], v[50:53], v[138:141], v[2:5]
	v_mfma_f32_16x16x32_bf16 v[18:21], v[50:53], v[142:145], v[18:21]
	ds_read_b128 v[50:53], v234 offset:23040
	s_waitcnt lgkmcnt(3)
	v_mfma_f32_16x16x32_bf16 v[6:9], v[54:57], v[138:141], v[6:9]
	v_mfma_f32_16x16x32_bf16 v[22:25], v[54:57], v[142:145], v[22:25]
	ds_read_b128 v[54:57], v234 offset:23104
	s_waitcnt lgkmcnt(3)
	v_mfma_f32_16x16x32_bf16 v[10:13], v[58:61], v[138:141], v[10:13]
	v_mfma_f32_16x16x32_bf16 v[26:29], v[58:61], v[142:145], v[26:29]
	ds_read_b128 v[58:61], v234 offset:25344
	s_waitcnt lgkmcnt(3)
	v_mfma_f32_16x16x32_bf16 v[14:17], v[62:65], v[138:141], v[14:17]
	v_mfma_f32_16x16x32_bf16 v[30:33], v[62:65], v[142:145], v[30:33]
	ds_read_b128 v[62:65], v234 offset:25408
	s_waitcnt lgkmcnt(3)
	v_mfma_f32_16x16x32_bf16 v[34:37], v[50:53], v[66:69], 0
	v_mfma_f32_16x16x32_bf16 v[42:45], v[50:53], v[74:77], 0
	s_waitcnt lgkmcnt(2)
	v_mfma_f32_16x16x32_bf16 v[34:37], v[54:57], v[70:73], v[34:37]
	v_mfma_f32_16x16x32_bf16 v[42:45], v[54:57], v[78:81], v[42:45]
	s_waitcnt lgkmcnt(1)
	v_mfma_f32_16x16x32_bf16 v[38:41], v[58:61], v[66:69], 0
	v_mfma_f32_16x16x32_bf16 v[46:49], v[58:61], v[74:77], 0
	s_waitcnt lgkmcnt(0)
	v_mfma_f32_16x16x32_bf16 v[38:41], v[62:65], v[70:73], v[38:41]
	v_mfma_f32_16x16x32_bf16 v[46:49], v[62:65], v[78:81], v[46:49]
	ds_read_b128 v[50:53], v234 offset:27712
	ds_read_b128 v[54:57], v234 offset:30016
	ds_read_b128 v[58:61], v234 offset:32320
	ds_read_b128 v[62:65], v234 offset:34624
	v_fma_f32 v34, v34, s48, v100
	v_fma_f32 v35, v35, s48, v100
	v_fma_f32 v36, v36, s48, v100
	v_fma_f32 v37, v37, s48, v100
	v_fma_f32 v38, v38, s48, v100
	v_fma_f32 v39, v39, s48, v100
	v_fma_f32 v40, v40, s48, v100
	v_fma_f32 v41, v41, s48, v100
	v_fma_f32 v42, v42, s48, v100
	v_fma_f32 v43, v43, s48, v100
	v_fma_f32 v44, v44, s48, v100
	v_fma_f32 v45, v45, s48, v100
	v_fma_f32 v46, v46, s48, v100
	v_fma_f32 v47, v47, s48, v100
	v_fma_f32 v48, v48, s48, v100
	v_fma_f32 v49, v49, s48, v100
	v_exp_f32_e32 v34, v34
	v_exp_f32_e32 v35, v35
	v_exp_f32_e32 v36, v36
	v_exp_f32_e32 v37, v37
	v_exp_f32_e32 v38, v38
	v_exp_f32_e32 v39, v39
	v_exp_f32_e32 v40, v40
	v_exp_f32_e32 v41, v41
	v_exp_f32_e32 v42, v42
	v_exp_f32_e32 v43, v43
	v_exp_f32_e32 v44, v44
	v_exp_f32_e32 v45, v45
	v_exp_f32_e32 v46, v46
	v_exp_f32_e32 v47, v47
	v_exp_f32_e32 v48, v48
	v_exp_f32_e32 v49, v49
	v_add_f32_e32 v138, v34, v35
	v_add_f32_e32 v139, v36, v37
	v_add_f32_e32 v138, v138, v38
	v_add_f32_e32 v139, v139, v39
	v_add_f32_e32 v138, v138, v40
	v_add_f32_e32 v139, v139, v41
	v_add_f32_e32 v138, v138, v139
	v_add_f32_e32 v129, v129, v138
	v_add_f32_e32 v140, v42, v43
	v_add_f32_e32 v141, v44, v45
	v_add_f32_e32 v140, v140, v46
	v_add_f32_e32 v141, v141, v47
	v_add_f32_e32 v140, v140, v48
	v_add_f32_e32 v141, v141, v49
	v_add_f32_e32 v140, v140, v141
	v_add_f32_e32 v235, v235, v140
	v_cvt_pk_bf16_f32 v138, v34, v35
	v_cvt_pk_bf16_f32 v139, v36, v37
	v_cvt_pk_bf16_f32 v140, v38, v39
	v_cvt_pk_bf16_f32 v141, v40, v41
	v_cvt_pk_bf16_f32 v142, v42, v43
	v_cvt_pk_bf16_f32 v143, v44, v45
	v_cvt_pk_bf16_f32 v144, v46, v47
	v_cvt_pk_bf16_f32 v145, v48, v49
	s_waitcnt lgkmcnt(3)
	v_mfma_f32_16x16x32_bf16 v[2:5], v[50:53], v[138:141], v[2:5]
	v_mfma_f32_16x16x32_bf16 v[18:21], v[50:53], v[142:145], v[18:21]
	s_waitcnt lgkmcnt(2)
	v_mfma_f32_16x16x32_bf16 v[6:9], v[54:57], v[138:141], v[6:9]
	v_mfma_f32_16x16x32_bf16 v[22:25], v[54:57], v[142:145], v[22:25]
	s_waitcnt lgkmcnt(1)
	v_mfma_f32_16x16x32_bf16 v[10:13], v[58:61], v[138:141], v[10:13]
	v_mfma_f32_16x16x32_bf16 v[26:29], v[58:61], v[142:145], v[26:29]
	s_waitcnt lgkmcnt(0)
	v_mfma_f32_16x16x32_bf16 v[14:17], v[62:65], v[138:141], v[14:17]
	v_mfma_f32_16x16x32_bf16 v[30:33], v[62:65], v[142:145], v[30:33]
	s_branch .Lsb16_wend_1
.Lsb16_wm_1:
	s_add_i32 s83, s59, s25
	s_lshl_b32 s83, s83, 6
	s_movk_i32 s58, 0x1ff
	s_waitcnt lgkmcnt(7)
	v_mfma_f32_16x16x32_bf16 v[34:37], v[50:53], v[66:69], 0
	v_mfma_f32_16x16x32_bf16 v[42:45], v[50:53], v[74:77], 0
	s_waitcnt lgkmcnt(6)
	v_mfma_f32_16x16x32_bf16 v[34:37], v[54:57], v[70:73], v[34:37]
	v_mfma_f32_16x16x32_bf16 v[42:45], v[54:57], v[78:81], v[42:45]
	s_waitcnt lgkmcnt(5)
	v_mfma_f32_16x16x32_bf16 v[38:41], v[58:61], v[66:69], 0
	v_mfma_f32_16x16x32_bf16 v[46:49], v[58:61], v[74:77], 0
	s_waitcnt lgkmcnt(4)
	v_mfma_f32_16x16x32_bf16 v[38:41], v[62:65], v[70:73], v[38:41]
	v_mfma_f32_16x16x32_bf16 v[46:49], v[62:65], v[78:81], v[46:49]
	ds_read_b128 v[50:53], v234 offset:27648
	ds_read_b128 v[54:57], v234 offset:29952
	ds_read_b128 v[58:61], v234 offset:32256
	ds_read_b128 v[62:65], v234 offset:34560
	v_subrev_u32_e32 v146, s83, v239
	v_add_u32_e32 v145, 2, v146
	v_fma_f32 v34, v34, s48, v100
	v_fma_f32 v35, v35, s48, v100
	v_fma_f32 v36, v36, s48, v100
	v_fma_f32 v37, v37, s48, v100
	v_fma_f32 v38, v38, s48, v100
	v_fma_f32 v39, v39, s48, v100
	v_fma_f32 v40, v40, s48, v100
	v_fma_f32 v41, v41, s48, v100
	v_fma_f32 v42, v42, s48, v100
	v_fma_f32 v43, v43, s48, v100
	v_fma_f32 v44, v44, s48, v100
	v_fma_f32 v45, v45, s48, v100
	v_fma_f32 v46, v46, s48, v100
	v_fma_f32 v47, v47, s48, v100
	v_fma_f32 v48, v48, s48, v100
	v_fma_f32 v49, v49, s48, v100
	v_subrev_u32_e32 v136, 0, v146
	v_subrev_u32_e32 v137, 1, v146
	v_cmp_ge_u32_e32 vcc, 0x1ff, v136
	v_cmp_ge_u32_e64 s[28:29], s58, v137
	s_nop 0
	v_cndmask_b32_e32 v34, v213, v34, vcc
	v_cndmask_b32_e64 v35, v213, v35, s[28:29]
	v_subrev_u32_e32 v136, 2, v146
	v_subrev_u32_e32 v137, 3, v146
	v_cmp_ge_u32_e32 vcc, 0x1ff, v136
	v_cmp_ge_u32_e64 s[28:29], s58, v137
	s_nop 0
	v_cndmask_b32_e32 v36, v213, v36, vcc
	v_cndmask_b32_e64 v37, v213, v37, s[28:29]
	v_subrev_u32_e32 v136, 16, v146
	v_subrev_u32_e32 v137, 17, v146
	v_cmp_ge_u32_e32 vcc, 0x1ff, v136
	v_cmp_ge_u32_e64 s[28:29], s58, v137
	s_nop 0
	v_cndmask_b32_e32 v38, v213, v38, vcc
	v_cndmask_b32_e64 v39, v213, v39, s[28:29]
	v_subrev_u32_e32 v136, 18, v146
	v_subrev_u32_e32 v137, 19, v146
	v_cmp_ge_u32_e32 vcc, 0x1ff, v136
	v_cmp_ge_u32_e64 s[28:29], s58, v137
	s_nop 0
	v_cndmask_b32_e32 v40, v213, v40, vcc
	v_cndmask_b32_e64 v41, v213, v41, s[28:29]
	v_subrev_u32_e32 v136, 0, v145
	v_subrev_u32_e32 v137, 1, v145
	v_cmp_ge_u32_e32 vcc, 0x1ff, v136
	v_cmp_ge_u32_e64 s[28:29], s58, v137
	s_nop 0
	v_cndmask_b32_e32 v42, v213, v42, vcc
	v_cndmask_b32_e64 v43, v213, v43, s[28:29]
	v_subrev_u32_e32 v136, 2, v145
	v_subrev_u32_e32 v137, 3, v145
	v_cmp_ge_u32_e32 vcc, 0x1ff, v136
	v_cmp_ge_u32_e64 s[28:29], s58, v137
	s_nop 0
	v_cndmask_b32_e32 v44, v213, v44, vcc
	v_cndmask_b32_e64 v45, v213, v45, s[28:29]
	v_subrev_u32_e32 v136, 16, v145
	v_subrev_u32_e32 v137, 17, v145
	v_cmp_ge_u32_e32 vcc, 0x1ff, v136
	v_cmp_ge_u32_e64 s[28:29], s58, v137
	s_nop 0
	v_cndmask_b32_e32 v46, v213, v46, vcc
	v_cndmask_b32_e64 v47, v213, v47, s[28:29]
	v_subrev_u32_e32 v136, 18, v145
	v_subrev_u32_e32 v137, 19, v145
	v_cmp_ge_u32_e32 vcc, 0x1ff, v136
	v_cmp_ge_u32_e64 s[28:29], s58, v137
	s_nop 0
	v_cndmask_b32_e32 v48, v213, v48, vcc
	v_cndmask_b32_e64 v49, v213, v49, s[28:29]
	v_exp_f32_e32 v34, v34
	v_exp_f32_e32 v35, v35
	v_exp_f32_e32 v36, v36
	v_exp_f32_e32 v37, v37
	v_exp_f32_e32 v38, v38
	v_exp_f32_e32 v39, v39
	v_exp_f32_e32 v40, v40
	v_exp_f32_e32 v41, v41
	v_exp_f32_e32 v42, v42
	v_exp_f32_e32 v43, v43
	v_exp_f32_e32 v44, v44
	v_exp_f32_e32 v45, v45
	v_exp_f32_e32 v46, v46
	v_exp_f32_e32 v47, v47
	v_exp_f32_e32 v48, v48
	v_exp_f32_e32 v49, v49
	v_add_f32_e32 v138, v34, v35
	v_add_f32_e32 v139, v36, v37
	v_add_f32_e32 v138, v138, v38
	v_add_f32_e32 v139, v139, v39
	v_add_f32_e32 v138, v138, v40
	v_add_f32_e32 v139, v139, v41
	v_add_f32_e32 v138, v138, v139
	v_add_f32_e32 v129, v129, v138
	v_add_f32_e32 v140, v42, v43
	v_add_f32_e32 v141, v44, v45
	v_add_f32_e32 v140, v140, v46
	v_add_f32_e32 v141, v141, v47
	v_add_f32_e32 v140, v140, v48
	v_add_f32_e32 v141, v141, v49
	v_add_f32_e32 v140, v140, v141
	v_add_f32_e32 v235, v235, v140
	v_cvt_pk_bf16_f32 v138, v34, v35
	v_cvt_pk_bf16_f32 v139, v36, v37
	v_cvt_pk_bf16_f32 v140, v38, v39
	v_cvt_pk_bf16_f32 v141, v40, v41
	v_cvt_pk_bf16_f32 v142, v42, v43
	v_cvt_pk_bf16_f32 v143, v44, v45
	v_cvt_pk_bf16_f32 v144, v46, v47
	v_cvt_pk_bf16_f32 v145, v48, v49
	s_waitcnt lgkmcnt(3)
	v_mfma_f32_16x16x32_bf16 v[2:5], v[50:53], v[138:141], v[2:5]
	v_mfma_f32_16x16x32_bf16 v[18:21], v[50:53], v[142:145], v[18:21]
	ds_read_b128 v[50:53], v234 offset:23040
	s_waitcnt lgkmcnt(3)
	v_mfma_f32_16x16x32_bf16 v[6:9], v[54:57], v[138:141], v[6:9]
	v_mfma_f32_16x16x32_bf16 v[22:25], v[54:57], v[142:145], v[22:25]
	ds_read_b128 v[54:57], v234 offset:23104
	s_waitcnt lgkmcnt(3)
	v_mfma_f32_16x16x32_bf16 v[10:13], v[58:61], v[138:141], v[10:13]
	v_mfma_f32_16x16x32_bf16 v[26:29], v[58:61], v[142:145], v[26:29]
	ds_read_b128 v[58:61], v234 offset:25344
	s_waitcnt lgkmcnt(3)
	v_mfma_f32_16x16x32_bf16 v[14:17], v[62:65], v[138:141], v[14:17]
	v_mfma_f32_16x16x32_bf16 v[30:33], v[62:65], v[142:145], v[30:33]
	ds_read_b128 v[62:65], v234 offset:25408
	s_waitcnt lgkmcnt(3)
	v_mfma_f32_16x16x32_bf16 v[34:37], v[50:53], v[66:69], 0
	v_mfma_f32_16x16x32_bf16 v[42:45], v[50:53], v[74:77], 0
	s_waitcnt lgkmcnt(2)
	v_mfma_f32_16x16x32_bf16 v[34:37], v[54:57], v[70:73], v[34:37]
	v_mfma_f32_16x16x32_bf16 v[42:45], v[54:57], v[78:81], v[42:45]
	s_waitcnt lgkmcnt(1)
	v_mfma_f32_16x16x32_bf16 v[38:41], v[58:61], v[66:69], 0
	v_mfma_f32_16x16x32_bf16 v[46:49], v[58:61], v[74:77], 0
	s_waitcnt lgkmcnt(0)
	v_mfma_f32_16x16x32_bf16 v[38:41], v[62:65], v[70:73], v[38:41]
	v_mfma_f32_16x16x32_bf16 v[46:49], v[62:65], v[78:81], v[46:49]
	ds_read_b128 v[50:53], v234 offset:27712
	ds_read_b128 v[54:57], v234 offset:30016
	ds_read_b128 v[58:61], v234 offset:32320
	ds_read_b128 v[62:65], v234 offset:34624
	v_subrev_u32_e32 v146, s83, v239
	v_add_u32_e32 v145, 2, v146
	v_fma_f32 v34, v34, s48, v100
	v_fma_f32 v35, v35, s48, v100
	v_fma_f32 v36, v36, s48, v100
	v_fma_f32 v37, v37, s48, v100
	v_fma_f32 v38, v38, s48, v100
	v_fma_f32 v39, v39, s48, v100
	v_fma_f32 v40, v40, s48, v100
	v_fma_f32 v41, v41, s48, v100
	v_fma_f32 v42, v42, s48, v100
	v_fma_f32 v43, v43, s48, v100
	v_fma_f32 v44, v44, s48, v100
	v_fma_f32 v45, v45, s48, v100
	v_fma_f32 v46, v46, s48, v100
	v_fma_f32 v47, v47, s48, v100
	v_fma_f32 v48, v48, s48, v100
	v_fma_f32 v49, v49, s48, v100
	v_subrev_u32_e32 v136, 32, v146
	v_subrev_u32_e32 v137, 33, v146
	v_cmp_ge_u32_e32 vcc, 0x1ff, v136
	v_cmp_ge_u32_e64 s[28:29], s58, v137
	s_nop 0
	v_cndmask_b32_e32 v34, v213, v34, vcc
	v_cndmask_b32_e64 v35, v213, v35, s[28:29]
	v_subrev_u32_e32 v136, 34, v146
	v_subrev_u32_e32 v137, 35, v146
	v_cmp_ge_u32_e32 vcc, 0x1ff, v136
	v_cmp_ge_u32_e64 s[28:29], s58, v137
	s_nop 0
	v_cndmask_b32_e32 v36, v213, v36, vcc
	v_cndmask_b32_e64 v37, v213, v37, s[28:29]
	v_subrev_u32_e32 v136, 48, v146
	v_subrev_u32_e32 v137, 49, v146
	v_cmp_ge_u32_e32 vcc, 0x1ff, v136
	v_cmp_ge_u32_e64 s[28:29], s58, v137
	s_nop 0
	v_cndmask_b32_e32 v38, v213, v38, vcc
	v_cndmask_b32_e64 v39, v213, v39, s[28:29]
	v_subrev_u32_e32 v136, 50, v146
	v_subrev_u32_e32 v137, 51, v146
	v_cmp_ge_u32_e32 vcc, 0x1ff, v136
	v_cmp_ge_u32_e64 s[28:29], s58, v137
	s_nop 0
	v_cndmask_b32_e32 v40, v213, v40, vcc
	v_cndmask_b32_e64 v41, v213, v41, s[28:29]
	v_subrev_u32_e32 v136, 32, v145
	v_subrev_u32_e32 v137, 33, v145
	v_cmp_ge_u32_e32 vcc, 0x1ff, v136
	v_cmp_ge_u32_e64 s[28:29], s58, v137
	s_nop 0
	v_cndmask_b32_e32 v42, v213, v42, vcc
	v_cndmask_b32_e64 v43, v213, v43, s[28:29]
	v_subrev_u32_e32 v136, 34, v145
	v_subrev_u32_e32 v137, 35, v145
	v_cmp_ge_u32_e32 vcc, 0x1ff, v136
	v_cmp_ge_u32_e64 s[28:29], s58, v137
	s_nop 0
	v_cndmask_b32_e32 v44, v213, v44, vcc
	v_cndmask_b32_e64 v45, v213, v45, s[28:29]
	v_subrev_u32_e32 v136, 48, v145
	v_subrev_u32_e32 v137, 49, v145
	v_cmp_ge_u32_e32 vcc, 0x1ff, v136
	v_cmp_ge_u32_e64 s[28:29], s58, v137
	s_nop 0
	v_cndmask_b32_e32 v46, v213, v46, vcc
	v_cndmask_b32_e64 v47, v213, v47, s[28:29]
	v_subrev_u32_e32 v136, 50, v145
	v_subrev_u32_e32 v137, 51, v145
	v_cmp_ge_u32_e32 vcc, 0x1ff, v136
	v_cmp_ge_u32_e64 s[28:29], s58, v137
	s_nop 0
	v_cndmask_b32_e32 v48, v213, v48, vcc
	v_cndmask_b32_e64 v49, v213, v49, s[28:29]
	v_exp_f32_e32 v34, v34
	v_exp_f32_e32 v35, v35
	v_exp_f32_e32 v36, v36
	v_exp_f32_e32 v37, v37
	v_exp_f32_e32 v38, v38
	v_exp_f32_e32 v39, v39
	v_exp_f32_e32 v40, v40
	v_exp_f32_e32 v41, v41
	v_exp_f32_e32 v42, v42
	v_exp_f32_e32 v43, v43
	v_exp_f32_e32 v44, v44
	v_exp_f32_e32 v45, v45
	v_exp_f32_e32 v46, v46
	v_exp_f32_e32 v47, v47
	v_exp_f32_e32 v48, v48
	v_exp_f32_e32 v49, v49
	v_add_f32_e32 v138, v34, v35
	v_add_f32_e32 v139, v36, v37
	v_add_f32_e32 v138, v138, v38
	v_add_f32_e32 v139, v139, v39
	v_add_f32_e32 v138, v138, v40
	v_add_f32_e32 v139, v139, v41
	v_add_f32_e32 v138, v138, v139
	v_add_f32_e32 v129, v129, v138
	v_add_f32_e32 v140, v42, v43
	v_add_f32_e32 v141, v44, v45
	v_add_f32_e32 v140, v140, v46
	v_add_f32_e32 v141, v141, v47
	v_add_f32_e32 v140, v140, v48
	v_add_f32_e32 v141, v141, v49
	v_add_f32_e32 v140, v140, v141
	v_add_f32_e32 v235, v235, v140
	v_cvt_pk_bf16_f32 v138, v34, v35
	v_cvt_pk_bf16_f32 v139, v36, v37
	v_cvt_pk_bf16_f32 v140, v38, v39
	v_cvt_pk_bf16_f32 v141, v40, v41
	v_cvt_pk_bf16_f32 v142, v42, v43
	v_cvt_pk_bf16_f32 v143, v44, v45
	v_cvt_pk_bf16_f32 v144, v46, v47
	v_cvt_pk_bf16_f32 v145, v48, v49
	s_waitcnt lgkmcnt(3)
	v_mfma_f32_16x16x32_bf16 v[2:5], v[50:53], v[138:141], v[2:5]
	v_mfma_f32_16x16x32_bf16 v[18:21], v[50:53], v[142:145], v[18:21]
	s_waitcnt lgkmcnt(2)
	v_mfma_f32_16x16x32_bf16 v[6:9], v[54:57], v[138:141], v[6:9]
	v_mfma_f32_16x16x32_bf16 v[22:25], v[54:57], v[142:145], v[22:25]
	s_waitcnt lgkmcnt(1)
	v_mfma_f32_16x16x32_bf16 v[10:13], v[58:61], v[138:141], v[10:13]
	v_mfma_f32_16x16x32_bf16 v[26:29], v[58:61], v[142:145], v[26:29]
	s_waitcnt lgkmcnt(0)
	v_mfma_f32_16x16x32_bf16 v[14:17], v[62:65], v[138:141], v[14:17]
	v_mfma_f32_16x16x32_bf16 v[30:33], v[62:65], v[142:145], v[30:33]

.Lsb16_wdone:
	v_mbcnt_lo_u32_b32 v40, -1, 0
	v_mbcnt_hi_u32_b32 v40, -1, v40
	v_xor_b32_e32 v41, 16, v40
	v_lshlrev_b32_e32 v41, 2, v41
	v_xor_b32_e32 v42, 32, v40
	v_lshlrev_b32_e32 v42, 2, v42
	ds_bpermute_b32 v43, v41, v129
	ds_bpermute_b32 v44, v41, v235
	s_waitcnt lgkmcnt(0)
	v_add_f32_e32 v129, v129, v43
	v_add_f32_e32 v235, v235, v44
	s_nop 0
	ds_bpermute_b32 v43, v42, v129
	ds_bpermute_b32 v44, v42, v235
	s_waitcnt lgkmcnt(0)
	v_add_f32_e32 v129, v129, v43
	v_add_f32_e32 v235, v235, v44
	v_div_scale_f32 v40, s[98:99], v129, v129, v133
	v_rcp_f32_e32 v41, v40
	v_div_scale_f32 v42, vcc, v133, v129, v133
	v_fma_f32 v43, -v40, v41, 1.0
	v_fmac_f32_e32 v41, v43, v41
	v_mul_f32_e32 v43, v42, v41
	v_fma_f32 v38, -v40, v43, v42
	v_fmac_f32_e32 v43, v38, v41
	v_fma_f32 v40, -v40, v43, v42
	v_div_fmas_f32 v40, v40, v41, v43
	v_div_fixup_f32 v38, v40, v129, v133
	v_div_scale_f32 v40, s[98:99], v235, v235, v148
	v_rcp_f32_e32 v41, v40
	v_div_scale_f32 v42, vcc, v148, v235, v148
	v_fma_f32 v43, -v40, v41, 1.0
	v_fmac_f32_e32 v41, v43, v41
	v_mul_f32_e32 v43, v42, v41
	v_fma_f32 v44, -v40, v43, v42
	v_fmac_f32_e32 v43, v44, v41
	v_fma_f32 v40, -v40, v43, v42
	v_div_fmas_f32 v40, v40, v41, v43
	v_div_fixup_f32 v44, v40, v235, v148
	ds_read2_b32 v[50:51], v237 offset0:0 offset1:1
	ds_read2_b32 v[52:53], v237 offset0:2 offset1:3
	ds_read2_b32 v[54:55], v237 offset0:16 offset1:17
	ds_read2_b32 v[56:57], v237 offset0:18 offset1:19
	ds_read2_b32 v[58:59], v237 offset0:32 offset1:33
	ds_read2_b32 v[60:61], v237 offset0:34 offset1:35
	ds_read2_b32 v[62:63], v237 offset0:48 offset1:49
	ds_read2_b32 v[64:65], v237 offset0:50 offset1:51
	s_waitcnt lgkmcnt(7)
	v_pk_fma_f32 v[50:51], v[2:3], v[38:39], v[50:51] op_sel_hi:[1,0,1]
	s_waitcnt lgkmcnt(6)
	v_pk_fma_f32 v[52:53], v[4:5], v[38:39], v[52:53] op_sel_hi:[1,0,1]
	s_waitcnt lgkmcnt(5)
	v_pk_fma_f32 v[54:55], v[6:7], v[38:39], v[54:55] op_sel_hi:[1,0,1]
	s_waitcnt lgkmcnt(4)
	v_pk_fma_f32 v[56:57], v[8:9], v[38:39], v[56:57] op_sel_hi:[1,0,1]
	s_waitcnt lgkmcnt(3)
	v_pk_fma_f32 v[58:59], v[10:11], v[38:39], v[58:59] op_sel_hi:[1,0,1]
	s_waitcnt lgkmcnt(2)
	v_pk_fma_f32 v[60:61], v[12:13], v[38:39], v[60:61] op_sel_hi:[1,0,1]
	s_waitcnt lgkmcnt(1)
	v_pk_fma_f32 v[62:63], v[14:15], v[38:39], v[62:63] op_sel_hi:[1,0,1]
	s_waitcnt lgkmcnt(0)
	v_pk_fma_f32 v[64:65], v[16:17], v[38:39], v[64:65] op_sel_hi:[1,0,1]
	ds_write2_b32 v237, v50, v51 offset0:0 offset1:1
	ds_write2_b32 v237, v52, v53 offset0:2 offset1:3
	ds_write2_b32 v237, v54, v55 offset0:16 offset1:17
	ds_write2_b32 v237, v56, v57 offset0:18 offset1:19
	ds_write2_b32 v237, v58, v59 offset0:32 offset1:33
	ds_write2_b32 v237, v60, v61 offset0:34 offset1:35
	ds_write2_b32 v237, v62, v63 offset0:48 offset1:49
	ds_write2_b32 v237, v64, v65 offset0:50 offset1:51
	ds_read2_b32 v[50:51], v238 offset0:0 offset1:1
	ds_read2_b32 v[52:53], v238 offset0:2 offset1:3
	ds_read2_b32 v[54:55], v238 offset0:16 offset1:17
	ds_read2_b32 v[56:57], v238 offset0:18 offset1:19
	ds_read2_b32 v[58:59], v238 offset0:32 offset1:33
	ds_read2_b32 v[60:61], v238 offset0:34 offset1:35
	ds_read2_b32 v[62:63], v238 offset0:48 offset1:49
	ds_read2_b32 v[64:65], v238 offset0:50 offset1:51
	s_waitcnt lgkmcnt(7)
	v_pk_fma_f32 v[50:51], v[18:19], v[44:45], v[50:51] op_sel_hi:[1,0,1]
	s_waitcnt lgkmcnt(6)
	v_pk_fma_f32 v[52:53], v[20:21], v[44:45], v[52:53] op_sel_hi:[1,0,1]
	s_waitcnt lgkmcnt(5)
	v_pk_fma_f32 v[54:55], v[22:23], v[44:45], v[54:55] op_sel_hi:[1,0,1]
	s_waitcnt lgkmcnt(4)
	v_pk_fma_f32 v[56:57], v[24:25], v[44:45], v[56:57] op_sel_hi:[1,0,1]
	s_waitcnt lgkmcnt(3)
	v_pk_fma_f32 v[58:59], v[26:27], v[44:45], v[58:59] op_sel_hi:[1,0,1]
	s_waitcnt lgkmcnt(2)
	v_pk_fma_f32 v[60:61], v[28:29], v[44:45], v[60:61] op_sel_hi:[1,0,1]
	s_waitcnt lgkmcnt(1)
	v_pk_fma_f32 v[62:63], v[30:31], v[44:45], v[62:63] op_sel_hi:[1,0,1]
	s_waitcnt lgkmcnt(0)
	v_pk_fma_f32 v[64:65], v[32:33], v[44:45], v[64:65] op_sel_hi:[1,0,1]
	ds_write2_b32 v238, v50, v51 offset0:0 offset1:1
	ds_write2_b32 v238, v52, v53 offset0:2 offset1:3
	ds_write2_b32 v238, v54, v55 offset0:16 offset1:17
	ds_write2_b32 v238, v56, v57 offset0:18 offset1:19
	ds_write2_b32 v238, v58, v59 offset0:32 offset1:33
	ds_write2_b32 v238, v60, v61 offset0:34 offset1:35
	ds_write2_b32 v238, v62, v63 offset0:48 offset1:49
	ds_write2_b32 v238, v64, v65 offset0:50 offset1:51
	v_subrev_u32_e32 v11, s68, v189
	v_lshlrev_b32_e32 v10, 6, v11
	s_add_i32 s20, s54, s67
	s_ashr_i32 s20, s20, 3
	v_and_or_b32 v2, s20, -16, v164
	v_or_b32_e32 v2, s55, v2
	v_ashrrev_i32_e32 v3, 31, v2
	v_lshlrev_b64 v[2:3], 14, v[2:3]
	v_readlane_b32 s20, v231, 24
	v_readlane_b32 s21, v231, 25
	s_nop 3
	v_lshl_add_u64 v[2:3], s[20:21], 0, v[2:3]
	s_mov_b64 s[20:21], 0
	v_mov_b32_e32 v4, v190
	v_mov_b32_e32 v5, v174
	v_mov_b32_e32 v6, v188
	s_waitcnt lgkmcnt(0)
	s_barrier
	s_branch .LBB0_2197
